# v59 + MFMA hand-off trim: in all five 8-phase GEMM K-loops s_setprio 1 (+ the repeated lgkmcnt(0)) moved before the phase barrier and s_setprio 0 after it
# baseline (speedup 1.0000x reference)
; #define PG8_STAGE(bufoff, gbase, voff) do { _Pragma("unroll") for (int _i = 0; _i < 2; ++_i) \
;         __builtin_amdgcn_global_load_lds((const unsigned*)((const char*)(gbase) + (voff)[_i]), (PG8_LAS unsigned*)(lds + (bufoff) + ldsw + _i * 8192), 16, 0, 0); } while (0)
; #define PG8_LDA(dst, b, h) do { _Pragma("unroll") for (int m = 0; m < 4; ++m) _Pragma("unroll") for (int k = 0; k < 2; ++k) dst[m][k] = *(const PG8_LAS bf16x8*)(lds + PG8_SA(b, h) + aoff + m * 2048 + k * 1024); } while (0)
; #define PG8_LDB(dst, b, h) do { _Pragma("unroll") for (int n = 0; n < 2; ++n) _Pragma("unroll") for (int k = 0; k < 2; ++k) dst[n][k] = *(const PG8_LAS bf16x8*)(lds + PG8_SB(b, h) + boff + n * 2048 + k * 1024); } while (0)
; #define PG8_MMA(ai, bj, At, Bt) do { __builtin_amdgcn_s_setprio(1); _Pragma("unroll") for (int m = 0; m < 4; ++m) _Pragma("unroll") for (int n = 0; n < 2; ++n) _Pragma("unroll") for (int k = 0; k < 2; ++k) \
;         acc[ai][bj][m][n] = __builtin_amdgcn_mfma_f32_16x16x32_bf16(Bt[n][k], At[m][k], acc[ai][bj][m][n], 0, 0, 0); __builtin_amdgcn_s_setprio(0); } while (0)
; #define PG8_WAIT_V(n) asm volatile("s_waitcnt vmcnt(" #n ")" ::: "memory")
; #define PG8_BAR __builtin_amdgcn_s_barrier()
; template <class Epi, class Sched, bool ALIGN_EPI = false, bool SP2 = false>
; __device__ __forceinline__ void gemm_phase(PG8_LAS unsigned char* lds, const Gemm g, const Sched& S, const Epi& E) {
;     ...
;         for (int t = 0; t < nt; t += 2) {
;             const bool last = (t == nt - 2);
;             const char* a1 = cA + (size_t)(t + 1) * kstep;
;             const char* a2 = last ? nA : cA + (size_t)(t + 2) * kstep; const char* b2 = last ? nB : cB + (size_t)(t + 2) * kstep;
;             const char* a3 = a2 + kstep; const char* b3 = b2 + kstep;
;             if (last && has_next) S.a_ready(nxt);
;             if constexpr (SP2) {
;             PG8_LDB(B0, 0, 0); PG8_LDB(B1, 0, 1); PG8_SCHED; PG8_LDA(At, 0, 0); PG8_STAGE(PG8_SA(1, 1), a1 + hstepA, voffA);
;             PG8_WAIT_V(8); PG8_WAIT_L(0); PG8_BAR; PG8_MMA(0, 0, At, B0); PG8_MMA(0, 1, At, B1); PG8_BAR; PG8_SCHED;
;             PG8_LDA(At, 0, 1); PG8_STAGE(PG8_SB(0, 0), b2, voffB); PG8_STAGE(PG8_SB(0, 1), b2 + hstepB, voffB); PG8_STAGE(PG8_SA(0, 0), a2, voffA);
;             PG8_WAIT_V(8); PG8_WAIT_L(0); PG8_BAR; PG8_MMA(1, 0, At, B0); PG8_MMA(1, 1, At, B1); PG8_BAR; PG8_SCHED;
.LBB0_358:
	s_add_u32 s34, s74, 0xfffc0080
	s_addc_u32 s35, s75, -1
	s_add_i32 s76, 0, 0x10000
	s_cmp_eq_u32 vcc_lo, 12
	s_cselect_b32 s35, s39, s35
	s_cselect_b32 s34, s51, s34
	s_cselect_b32 s61, s49, s97
	s_cselect_b32 s60, s71, s96
	s_add_i32 s78, 0, 0x14000
	v_add_u32_e32 v142, s76, v171
	v_add_u32_e32 v158, s78, v171
	ds_read_b128 v[130:133], v142
	ds_read_b128 v[134:137], v142 offset:1024
	ds_read_b128 v[138:141], v142 offset:2048
	ds_read_b128 v[142:145], v142 offset:3072
	ds_read_b128 v[146:149], v158
	ds_read_b128 v[150:153], v158 offset:1024
	ds_read_b128 v[154:157], v158 offset:2048
	ds_read_b128 v[158:161], v158 offset:3072
	v_lshl_add_u64 v[220:221], s[74:75], 0, v[176:177]
	s_add_i32 m0, s80, 0xc000
	ds_read_b128 v[186:189], v218
	ds_read_b128 v[190:193], v218 offset:1024
	ds_read_b128 v[194:197], v218 offset:2048
	ds_read_b128 v[198:201], v218 offset:3072
	ds_read_b128 v[202:205], v218 offset:4096
	ds_read_b128 v[206:209], v218 offset:5120
	ds_read_b128 v[210:213], v218 offset:6144
	ds_read_b128 v[214:217], v218 offset:7168
	global_load_lds_dwordx4 v[220:221], off
	v_lshl_add_u64 v[220:221], s[74:75], 0, v[178:179]
	s_add_i32 m0, s80, 0xe000
	s_nop 0
	global_load_lds_dwordx4 v[220:221], off
	s_waitcnt vmcnt(8)
	s_waitcnt lgkmcnt(0)
	s_setprio 1
	s_waitcnt lgkmcnt(0)
	s_barrier
	v_mfma_f32_16x16x32_bf16 v[126:129], v[130:133], v[186:189], v[126:129]
	v_mfma_f32_16x16x32_bf16 v[122:125], v[138:141], v[186:189], v[122:125]
	v_mfma_f32_16x16x32_bf16 v[110:113], v[130:133], v[194:197], v[110:113]
	v_mfma_f32_16x16x32_bf16 v[106:109], v[138:141], v[194:197], v[106:109]
	v_mfma_f32_16x16x32_bf16 v[94:97], v[130:133], v[202:205], v[94:97]
	v_mfma_f32_16x16x32_bf16 v[90:93], v[138:141], v[202:205], v[90:93]
	v_mfma_f32_16x16x32_bf16 v[78:81], v[130:133], v[210:213], v[78:81]
	v_mfma_f32_16x16x32_bf16 v[74:77], v[138:141], v[210:213], v[74:77]
	v_mfma_f32_16x16x32_bf16 v[126:129], v[134:137], v[190:193], v[126:129]
	v_mfma_f32_16x16x32_bf16 v[122:125], v[142:145], v[190:193], v[122:125]
	v_mfma_f32_16x16x32_bf16 v[110:113], v[134:137], v[198:201], v[110:113]
	v_mfma_f32_16x16x32_bf16 v[106:109], v[142:145], v[198:201], v[106:109]
	v_mfma_f32_16x16x32_bf16 v[94:97], v[134:137], v[206:209], v[94:97]
	v_mfma_f32_16x16x32_bf16 v[90:93], v[142:145], v[206:209], v[90:93]
	v_mfma_f32_16x16x32_bf16 v[78:81], v[134:137], v[214:217], v[78:81]
	v_mfma_f32_16x16x32_bf16 v[74:77], v[142:145], v[214:217], v[74:77]
	v_mfma_f32_16x16x32_bf16 v[118:121], v[146:149], v[186:189], v[118:121]
	v_mfma_f32_16x16x32_bf16 v[114:117], v[154:157], v[186:189], v[114:117]
	v_mfma_f32_16x16x32_bf16 v[102:105], v[146:149], v[194:197], v[102:105]
	v_mfma_f32_16x16x32_bf16 v[98:101], v[154:157], v[194:197], v[98:101]
	v_mfma_f32_16x16x32_bf16 v[86:89], v[146:149], v[202:205], v[86:89]
	v_mfma_f32_16x16x32_bf16 v[82:85], v[154:157], v[202:205], v[82:85]
	v_mfma_f32_16x16x32_bf16 v[70:73], v[146:149], v[210:213], v[70:73]
	v_mfma_f32_16x16x32_bf16 v[66:69], v[154:157], v[210:213], v[66:69]
	v_mfma_f32_16x16x32_bf16 v[118:121], v[150:153], v[190:193], v[118:121]
	v_mfma_f32_16x16x32_bf16 v[114:117], v[158:161], v[190:193], v[114:117]
	v_mfma_f32_16x16x32_bf16 v[102:105], v[150:153], v[198:201], v[102:105]
	v_mfma_f32_16x16x32_bf16 v[98:101], v[158:161], v[198:201], v[98:101]
	v_mfma_f32_16x16x32_bf16 v[86:89], v[150:153], v[206:209], v[86:89]
	v_mfma_f32_16x16x32_bf16 v[82:85], v[158:161], v[206:209], v[82:85]
	v_mfma_f32_16x16x32_bf16 v[70:73], v[150:153], v[214:217], v[70:73]
	v_mfma_f32_16x16x32_bf16 v[66:69], v[158:161], v[214:217], v[66:69]
	s_barrier
	s_setprio 0
	s_add_i32 s76, s76, s36
	v_lshl_add_u64 v[220:221], s[60:61], 0, v[164:165]
	s_mov_b32 m0, s76
	ds_read_b128 v[186:189], v218 offset:16384
	ds_read_b128 v[190:193], v218 offset:17408
	ds_read_b128 v[194:197], v218 offset:18432
	ds_read_b128 v[198:201], v218 offset:19456
	ds_read_b128 v[202:205], v218 offset:20480
	ds_read_b128 v[206:209], v218 offset:21504
	ds_read_b128 v[210:213], v218 offset:22528
	ds_read_b128 v[214:217], v218 offset:23552
	global_load_lds_dwordx4 v[220:221], off
	s_add_i32 m0, s76, 0x2000
	s_add_u32 s76, s60, 0x40000
	v_lshl_add_u64 v[234:235], s[60:61], 0, v[168:169]
	s_addc_u32 s77, s61, 0
	s_add_i32 s78, s78, s36
	global_load_lds_dwordx4 v[234:235], off
	v_lshl_add_u64 v[236:237], s[76:77], 0, v[164:165]
	s_mov_b32 m0, s78
	v_lshl_add_u64 v[238:239], s[34:35], 0, v[166:167]
	global_load_lds_dwordx4 v[236:237], off
	v_lshl_add_u64 v[236:237], s[76:77], 0, v[168:169]
	s_add_i32 m0, s78, 0x2000
	s_nop 0
	global_load_lds_dwordx4 v[236:237], off
	v_lshl_add_u64 v[236:237], s[34:35], 0, v[162:163]
	s_mov_b32 m0, s80
	s_nop 0
	global_load_lds_dwordx4 v[236:237], off
	s_mov_b32 m0, s81
	s_nop 0
	global_load_lds_dwordx4 v[238:239], off
	s_waitcnt vmcnt(8)
	s_waitcnt lgkmcnt(0)
	s_setprio 1
	s_waitcnt lgkmcnt(0)
	s_barrier
; #define PG8_STAGE(bufoff, gbase, voff) do { _Pragma("unroll") for (int _i = 0; _i < 2; ++_i) \
;         __builtin_amdgcn_global_load_lds((const unsigned*)((const char*)(gbase) + (voff)[_i]), (PG8_LAS unsigned*)(lds + (bufoff) + ldsw + _i * 8192), 16, 0, 0); } while (0)
; #define PG8_LDA(dst, b, h) do { _Pragma("unroll") for (int m = 0; m < 4; ++m) _Pragma("unroll") for (int k = 0; k < 2; ++k) dst[m][k] = *(const PG8_LAS bf16x8*)(lds + PG8_SA(b, h) + aoff + m * 2048 + k * 1024); } while (0)
; #define PG8_LDB(dst, b, h) do { _Pragma("unroll") for (int n = 0; n < 2; ++n) _Pragma("unroll") for (int k = 0; k < 2; ++k) dst[n][k] = *(const PG8_LAS bf16x8*)(lds + PG8_SB(b, h) + boff + n * 2048 + k * 1024); } while (0)
; #define PG8_MMA(ai, bj, At, Bt) do { __builtin_amdgcn_s_setprio(1); _Pragma("unroll") for (int m = 0; m < 4; ++m) _Pragma("unroll") for (int n = 0; n < 2; ++n) _Pragma("unroll") for (int k = 0; k < 2; ++k) \
;         acc[ai][bj][m][n] = __builtin_amdgcn_mfma_f32_16x16x32_bf16(Bt[n][k], At[m][k], acc[ai][bj][m][n], 0, 0, 0); __builtin_amdgcn_s_setprio(0); } while (0)
; #define PG8_WAIT_V(n) asm volatile("s_waitcnt vmcnt(" #n ")" ::: "memory")
; #define PG8_WAIT_L(n) asm volatile("s_waitcnt lgkmcnt(" #n ")" ::: "memory")
; #define PG8_BAR __builtin_amdgcn_s_barrier()
; #define PG8_SCHED __builtin_amdgcn_sched_barrier(0)
; template <class Epi, class Sched, bool ALIGN_EPI = false, bool SP2 = false>
; __device__ __forceinline__ void gemm_phase(PG8_LAS unsigned char* lds, const Gemm g, const Sched& S, const Epi& E) {
;     ...
;             PG8_WAIT_V(8); PG8_WAIT_L(0); PG8_BAR; PG8_MMA(1, 0, At, B0); PG8_MMA(1, 1, At, B1); PG8_BAR; PG8_SCHED;
;             PG8_LDB(B0, 1, 0); PG8_LDB(B1, 1, 1); PG8_SCHED; PG8_LDA(At, 1, 0); PG8_STAGE(PG8_SA(0, 1), a2 + hstepA, voffA);
;             PG8_WAIT_V(8); PG8_WAIT_L(0); PG8_BAR; PG8_MMA(0, 0, At, B0); PG8_MMA(0, 1, At, B1); PG8_BAR; PG8_SCHED;
	v_mfma_f32_16x16x32_bf16 v[62:65], v[130:133], v[186:189], v[62:65]
	v_mfma_f32_16x16x32_bf16 v[58:61], v[138:141], v[186:189], v[58:61]
	v_mfma_f32_16x16x32_bf16 v[46:49], v[130:133], v[194:197], v[46:49]
	v_mfma_f32_16x16x32_bf16 v[42:45], v[138:141], v[194:197], v[42:45]
	v_mfma_f32_16x16x32_bf16 v[30:33], v[130:133], v[202:205], v[30:33]
	v_mfma_f32_16x16x32_bf16 v[26:29], v[138:141], v[202:205], v[26:29]
	v_mfma_f32_16x16x32_bf16 v[14:17], v[130:133], v[210:213], v[14:17]
	v_mfma_f32_16x16x32_bf16 v[10:13], v[138:141], v[210:213], v[10:13]
	v_mfma_f32_16x16x32_bf16 v[62:65], v[134:137], v[190:193], v[62:65]
	v_mfma_f32_16x16x32_bf16 v[58:61], v[142:145], v[190:193], v[58:61]
	v_mfma_f32_16x16x32_bf16 v[46:49], v[134:137], v[198:201], v[46:49]
	v_mfma_f32_16x16x32_bf16 v[42:45], v[142:145], v[198:201], v[42:45]
	v_mfma_f32_16x16x32_bf16 v[30:33], v[134:137], v[206:209], v[30:33]
	v_mfma_f32_16x16x32_bf16 v[26:29], v[142:145], v[206:209], v[26:29]
	v_mfma_f32_16x16x32_bf16 v[14:17], v[134:137], v[214:217], v[14:17]
	v_mfma_f32_16x16x32_bf16 v[10:13], v[142:145], v[214:217], v[10:13]
	v_mfma_f32_16x16x32_bf16 v[54:57], v[146:149], v[186:189], v[54:57]
	v_mfma_f32_16x16x32_bf16 v[50:53], v[154:157], v[186:189], v[50:53]
	v_mfma_f32_16x16x32_bf16 v[38:41], v[146:149], v[194:197], v[38:41]
	v_mfma_f32_16x16x32_bf16 v[34:37], v[154:157], v[194:197], v[34:37]
	v_mfma_f32_16x16x32_bf16 v[22:25], v[146:149], v[202:205], v[22:25]
	v_mfma_f32_16x16x32_bf16 v[18:21], v[154:157], v[202:205], v[18:21]
	v_mfma_f32_16x16x32_bf16 v[6:9], v[146:149], v[210:213], v[6:9]
	v_mfma_f32_16x16x32_bf16 v[2:5], v[154:157], v[210:213], v[2:5]
	v_mfma_f32_16x16x32_bf16 v[54:57], v[150:153], v[190:193], v[54:57]
	v_mfma_f32_16x16x32_bf16 v[50:53], v[158:161], v[190:193], v[50:53]
	v_mfma_f32_16x16x32_bf16 v[38:41], v[150:153], v[198:201], v[38:41]
	v_mfma_f32_16x16x32_bf16 v[34:37], v[158:161], v[198:201], v[34:37]
	v_mfma_f32_16x16x32_bf16 v[22:25], v[150:153], v[206:209], v[22:25]
	v_mfma_f32_16x16x32_bf16 v[18:21], v[158:161], v[206:209], v[18:21]
	v_mfma_f32_16x16x32_bf16 v[6:9], v[150:153], v[214:217], v[6:9]
	v_mfma_f32_16x16x32_bf16 v[2:5], v[158:161], v[214:217], v[2:5]
	s_barrier
	s_setprio 0
	s_add_i32 s76, 0, 0x18000
	s_add_i32 s77, 0, 0x1c000
	v_add_u32_e32 v142, s76, v171
	v_add_u32_e32 v158, s77, v171
	ds_read_b128 v[130:133], v142
	ds_read_b128 v[134:137], v142 offset:1024
	ds_read_b128 v[138:141], v142 offset:2048
	ds_read_b128 v[142:145], v142 offset:3072
	ds_read_b128 v[146:149], v158
	ds_read_b128 v[150:153], v158 offset:1024
	ds_read_b128 v[154:157], v158 offset:2048
	ds_read_b128 v[158:161], v158 offset:3072
	s_add_u32 s34, s34, 0x40000
	s_addc_u32 s35, s35, 0
	s_mov_b32 m0, s89
	v_lshl_add_u64 v[240:241], s[34:35], 0, v[162:163]
	ds_read_b128 v[186:189], v218 offset:32768
	ds_read_b128 v[190:193], v218 offset:33792
	ds_read_b128 v[194:197], v218 offset:34816
	ds_read_b128 v[198:201], v218 offset:35840
	ds_read_b128 v[202:205], v218 offset:36864
	ds_read_b128 v[206:209], v218 offset:37888
	ds_read_b128 v[210:213], v218 offset:38912
	ds_read_b128 v[214:217], v218 offset:39936
	global_load_lds_dwordx4 v[240:241], off
	v_lshl_add_u64 v[240:241], s[34:35], 0, v[166:167]
	s_mov_b32 m0, s90
	s_nop 0
	global_load_lds_dwordx4 v[240:241], off
	s_waitcnt vmcnt(8)
	s_waitcnt lgkmcnt(0)
	s_setprio 1
	s_waitcnt lgkmcnt(0)
	s_barrier
	v_mfma_f32_16x16x32_bf16 v[126:129], v[130:133], v[186:189], v[126:129]
	v_mfma_f32_16x16x32_bf16 v[122:125], v[138:141], v[186:189], v[122:125]
	v_mfma_f32_16x16x32_bf16 v[110:113], v[130:133], v[194:197], v[110:113]
	v_mfma_f32_16x16x32_bf16 v[106:109], v[138:141], v[194:197], v[106:109]
	v_mfma_f32_16x16x32_bf16 v[94:97], v[130:133], v[202:205], v[94:97]
	v_mfma_f32_16x16x32_bf16 v[90:93], v[138:141], v[202:205], v[90:93]
	v_mfma_f32_16x16x32_bf16 v[78:81], v[130:133], v[210:213], v[78:81]
	v_mfma_f32_16x16x32_bf16 v[74:77], v[138:141], v[210:213], v[74:77]
	v_mfma_f32_16x16x32_bf16 v[126:129], v[134:137], v[190:193], v[126:129]
	v_mfma_f32_16x16x32_bf16 v[122:125], v[142:145], v[190:193], v[122:125]
	v_mfma_f32_16x16x32_bf16 v[110:113], v[134:137], v[198:201], v[110:113]
	v_mfma_f32_16x16x32_bf16 v[106:109], v[142:145], v[198:201], v[106:109]
	v_mfma_f32_16x16x32_bf16 v[94:97], v[134:137], v[206:209], v[94:97]
	v_mfma_f32_16x16x32_bf16 v[90:93], v[142:145], v[206:209], v[90:93]
	v_mfma_f32_16x16x32_bf16 v[78:81], v[134:137], v[214:217], v[78:81]
	v_mfma_f32_16x16x32_bf16 v[74:77], v[142:145], v[214:217], v[74:77]
	v_mfma_f32_16x16x32_bf16 v[118:121], v[146:149], v[186:189], v[118:121]
	v_mfma_f32_16x16x32_bf16 v[114:117], v[154:157], v[186:189], v[114:117]
	v_mfma_f32_16x16x32_bf16 v[102:105], v[146:149], v[194:197], v[102:105]
	v_mfma_f32_16x16x32_bf16 v[98:101], v[154:157], v[194:197], v[98:101]
	v_mfma_f32_16x16x32_bf16 v[86:89], v[146:149], v[202:205], v[86:89]
	v_mfma_f32_16x16x32_bf16 v[82:85], v[154:157], v[202:205], v[82:85]
	v_mfma_f32_16x16x32_bf16 v[70:73], v[146:149], v[210:213], v[70:73]
	v_mfma_f32_16x16x32_bf16 v[66:69], v[154:157], v[210:213], v[66:69]
	v_mfma_f32_16x16x32_bf16 v[118:121], v[150:153], v[190:193], v[118:121]
	v_mfma_f32_16x16x32_bf16 v[114:117], v[158:161], v[190:193], v[114:117]
	v_mfma_f32_16x16x32_bf16 v[102:105], v[150:153], v[198:201], v[102:105]
	v_mfma_f32_16x16x32_bf16 v[98:101], v[158:161], v[198:201], v[98:101]
	v_mfma_f32_16x16x32_bf16 v[86:89], v[150:153], v[206:209], v[86:89]
	v_mfma_f32_16x16x32_bf16 v[82:85], v[158:161], v[206:209], v[82:85]
	v_mfma_f32_16x16x32_bf16 v[70:73], v[150:153], v[214:217], v[70:73]
	v_mfma_f32_16x16x32_bf16 v[66:69], v[158:161], v[214:217], v[66:69]
	s_barrier
; #define PG8_STAGE(bufoff, gbase, voff) do { _Pragma("unroll") for (int _i = 0; _i < 2; ++_i) \
;         __builtin_amdgcn_global_load_lds((const unsigned*)((const char*)(gbase) + (voff)[_i]), (PG8_LAS unsigned*)(lds + (bufoff) + ldsw + _i * 8192), 16, 0, 0); } while (0)
; #define PG8_LDA(dst, b, h) do { _Pragma("unroll") for (int m = 0; m < 4; ++m) _Pragma("unroll") for (int k = 0; k < 2; ++k) dst[m][k] = *(const PG8_LAS bf16x8*)(lds + PG8_SA(b, h) + aoff + m * 2048 + k * 1024); } while (0)
; #define PG8_MMA(ai, bj, At, Bt) do { __builtin_amdgcn_s_setprio(1); _Pragma("unroll") for (int m = 0; m < 4; ++m) _Pragma("unroll") for (int n = 0; n < 2; ++n) _Pragma("unroll") for (int k = 0; k < 2; ++k) \
;         acc[ai][bj][m][n] = __builtin_amdgcn_mfma_f32_16x16x32_bf16(Bt[n][k], At[m][k], acc[ai][bj][m][n], 0, 0, 0); __builtin_amdgcn_s_setprio(0); } while (0)
; #define PG8_WAIT_V(n) asm volatile("s_waitcnt vmcnt(" #n ")" ::: "memory")
; #define PG8_WAIT_L(n) asm volatile("s_waitcnt lgkmcnt(" #n ")" ::: "memory")
; #define PG8_BAR __builtin_amdgcn_s_barrier()
; #define PG8_SCHED __builtin_amdgcn_sched_barrier(0)
; template <class Epi, class Sched, bool ALIGN_EPI = false, bool SP2 = false>
; __device__ __forceinline__ void gemm_phase(PG8_LAS unsigned char* lds, const Gemm g, const Sched& S, const Epi& E) {
;     ...
;             PG8_WAIT_V(8); PG8_WAIT_L(0); PG8_BAR; PG8_MMA(0, 0, At, B0); PG8_MMA(0, 1, At, B1); PG8_BAR; PG8_SCHED;
;             PG8_LDA(At, 1, 1); PG8_STAGE(PG8_SB(1, 0), b3, voffB); PG8_STAGE(PG8_SB(1, 1), b3 + hstepB, voffB); PG8_STAGE(PG8_SA(1, 0), a3, voffA);
;             PG8_WAIT_V(8); PG8_WAIT_L(0); PG8_BAR; PG8_MMA(1, 0, At, B0); PG8_MMA(1, 1, At, B1); PG8_BAR; PG8_SCHED;
;     ...
;         if constexpr (ALIGN_EPI) { if (wr == 0) PG8_BAR; }
	s_setprio 0
	s_add_i32 s34, s76, s36
	v_lshl_add_u64 v[220:221], v[220:221], 0, s[62:63]
	s_mov_b32 m0, s34
	ds_read_b128 v[186:189], v218 offset:49152
	ds_read_b128 v[190:193], v218 offset:50176
	ds_read_b128 v[194:197], v218 offset:51200
	ds_read_b128 v[198:201], v218 offset:52224
	ds_read_b128 v[202:205], v218 offset:53248
	ds_read_b128 v[206:209], v218 offset:54272
	ds_read_b128 v[210:213], v218 offset:55296
	ds_read_b128 v[214:217], v218 offset:56320
	global_load_lds_dwordx4 v[220:221], off
	s_add_i32 m0, s34, 0x2000
	s_add_u32 s34, s60, 0x40080
	v_lshl_add_u64 v[220:221], v[234:235], 0, s[62:63]
	s_addc_u32 s35, s61, 0
	s_add_i32 s60, s77, s36
	global_load_lds_dwordx4 v[220:221], off
	v_lshl_add_u64 v[220:221], s[34:35], 0, v[164:165]
	s_mov_b32 m0, s60
	s_nop 0
	global_load_lds_dwordx4 v[220:221], off
	v_lshl_add_u64 v[220:221], s[34:35], 0, v[168:169]
	s_add_i32 m0, s60, 0x2000
	s_nop 0
	global_load_lds_dwordx4 v[220:221], off
	v_lshl_add_u64 v[220:221], v[236:237], 0, s[62:63]
	s_mov_b32 m0, s91
	s_nop 0
	global_load_lds_dwordx4 v[220:221], off
	v_lshl_add_u64 v[220:221], v[238:239], 0, s[62:63]
	s_mov_b32 m0, s92
	s_nop 0
	global_load_lds_dwordx4 v[220:221], off
	s_waitcnt vmcnt(8)
	s_waitcnt lgkmcnt(0)
	s_setprio 1
	s_waitcnt lgkmcnt(0)
	s_barrier
	v_mfma_f32_16x16x32_bf16 v[62:65], v[130:133], v[186:189], v[62:65]
	v_mfma_f32_16x16x32_bf16 v[58:61], v[138:141], v[186:189], v[58:61]
	v_mfma_f32_16x16x32_bf16 v[46:49], v[130:133], v[194:197], v[46:49]
	v_mfma_f32_16x16x32_bf16 v[42:45], v[138:141], v[194:197], v[42:45]
	v_mfma_f32_16x16x32_bf16 v[30:33], v[130:133], v[202:205], v[30:33]
	v_mfma_f32_16x16x32_bf16 v[26:29], v[138:141], v[202:205], v[26:29]
	v_mfma_f32_16x16x32_bf16 v[14:17], v[130:133], v[210:213], v[14:17]
	v_mfma_f32_16x16x32_bf16 v[10:13], v[138:141], v[210:213], v[10:13]
	v_mfma_f32_16x16x32_bf16 v[62:65], v[134:137], v[190:193], v[62:65]
	v_mfma_f32_16x16x32_bf16 v[58:61], v[142:145], v[190:193], v[58:61]
	v_mfma_f32_16x16x32_bf16 v[46:49], v[134:137], v[198:201], v[46:49]
	v_mfma_f32_16x16x32_bf16 v[42:45], v[142:145], v[198:201], v[42:45]
	v_mfma_f32_16x16x32_bf16 v[30:33], v[134:137], v[206:209], v[30:33]
	v_mfma_f32_16x16x32_bf16 v[26:29], v[142:145], v[206:209], v[26:29]
	v_mfma_f32_16x16x32_bf16 v[14:17], v[134:137], v[214:217], v[14:17]
	v_mfma_f32_16x16x32_bf16 v[10:13], v[142:145], v[214:217], v[10:13]
	v_mfma_f32_16x16x32_bf16 v[54:57], v[146:149], v[186:189], v[54:57]
	v_mfma_f32_16x16x32_bf16 v[50:53], v[154:157], v[186:189], v[50:53]
	v_mfma_f32_16x16x32_bf16 v[38:41], v[146:149], v[194:197], v[38:41]
	v_mfma_f32_16x16x32_bf16 v[34:37], v[154:157], v[194:197], v[34:37]
	v_mfma_f32_16x16x32_bf16 v[22:25], v[146:149], v[202:205], v[22:25]
	v_mfma_f32_16x16x32_bf16 v[18:21], v[154:157], v[202:205], v[18:21]
	v_mfma_f32_16x16x32_bf16 v[6:9], v[146:149], v[210:213], v[6:9]
	v_mfma_f32_16x16x32_bf16 v[2:5], v[154:157], v[210:213], v[2:5]
	v_mfma_f32_16x16x32_bf16 v[54:57], v[150:153], v[190:193], v[54:57]
	v_mfma_f32_16x16x32_bf16 v[50:53], v[158:161], v[190:193], v[50:53]
	v_mfma_f32_16x16x32_bf16 v[38:41], v[150:153], v[198:201], v[38:41]
	v_mfma_f32_16x16x32_bf16 v[34:37], v[158:161], v[198:201], v[34:37]
	v_mfma_f32_16x16x32_bf16 v[22:25], v[150:153], v[206:209], v[22:25]
	v_mfma_f32_16x16x32_bf16 v[18:21], v[158:161], v[206:209], v[18:21]
	v_mfma_f32_16x16x32_bf16 v[6:9], v[150:153], v[214:217], v[6:9]
	v_mfma_f32_16x16x32_bf16 v[2:5], v[158:161], v[214:217], v[2:5]
	s_barrier
	s_setprio 0
	s_add_i32 vcc_lo, vcc_lo, 2
	s_add_u32 s74, s74, 0x100
	s_addc_u32 s75, s75, 0
	s_add_u32 s96, s96, 0x100
	s_addc_u32 s97, s97, 0
	s_cmp_gt_u32 vcc_lo, 13
	s_cbranch_scc0 .LBB0_358
	s_and_b64 vcc, exec, s[46:47]
	s_cbranch_vccz .LBB0_361
	s_barrier

; #define PG8_STAGE(bufoff, gbase, voff) do { _Pragma("unroll") for (int _i = 0; _i < 2; ++_i) \
;         __builtin_amdgcn_global_load_lds((const unsigned*)((const char*)(gbase) + (voff)[_i]), (PG8_LAS unsigned*)(lds + (bufoff) + ldsw + _i * 8192), 16, 0, 0); } while (0)
; #define PG8_LDA(dst, b, h) do { _Pragma("unroll") for (int m = 0; m < 4; ++m) _Pragma("unroll") for (int k = 0; k < 2; ++k) dst[m][k] = *(const PG8_LAS bf16x8*)(lds + PG8_SA(b, h) + aoff + m * 2048 + k * 1024); } while (0)
; #define PG8_LDB(dst, b, h) do { _Pragma("unroll") for (int n = 0; n < 2; ++n) _Pragma("unroll") for (int k = 0; k < 2; ++k) dst[n][k] = *(const PG8_LAS bf16x8*)(lds + PG8_SB(b, h) + boff + n * 2048 + k * 1024); } while (0)
; #define PG8_MMA(ai, bj, At, Bt) do { __builtin_amdgcn_s_setprio(1); _Pragma("unroll") for (int m = 0; m < 4; ++m) _Pragma("unroll") for (int n = 0; n < 2; ++n) _Pragma("unroll") for (int k = 0; k < 2; ++k) \
;         acc[ai][bj][m][n] = __builtin_amdgcn_mfma_f32_16x16x32_bf16(Bt[n][k], At[m][k], acc[ai][bj][m][n], 0, 0, 0); __builtin_amdgcn_s_setprio(0); } while (0)
; #define PG8_WAIT_V(n) asm volatile("s_waitcnt vmcnt(" #n ")" ::: "memory")
; #define PG8_BAR __builtin_amdgcn_s_barrier()
; template <class Epi, class Sched, bool ALIGN_EPI = false, bool SP2 = false>
; __device__ __forceinline__ void gemm_phase(PG8_LAS unsigned char* lds, const Gemm g, const Sched& S, const Epi& E) {
;     ...
;         for (int t = 0; t < nt; t += 2) {
;             const bool last = (t == nt - 2);
;             const char* a1 = cA + (size_t)(t + 1) * kstep;
;             const char* a2 = last ? nA : cA + (size_t)(t + 2) * kstep; const char* b2 = last ? nB : cB + (size_t)(t + 2) * kstep;
;             const char* a3 = a2 + kstep; const char* b3 = b2 + kstep;
;             if (last && has_next) S.a_ready(nxt);
;             if constexpr (SP2) {
;             PG8_LDB(B0, 0, 0); PG8_LDB(B1, 0, 1); PG8_SCHED; PG8_LDA(At, 0, 0); PG8_STAGE(PG8_SA(1, 1), a1 + hstepA, voffA);
;             PG8_WAIT_V(8); PG8_WAIT_L(0); PG8_BAR; PG8_MMA(0, 0, At, B0); PG8_MMA(0, 1, At, B1); PG8_BAR; PG8_SCHED;
;             PG8_LDA(At, 0, 1); PG8_STAGE(PG8_SB(0, 0), b2, voffB); PG8_STAGE(PG8_SB(0, 1), b2 + hstepB, voffB); PG8_STAGE(PG8_SA(0, 0), a2, voffA);
;             PG8_WAIT_V(8); PG8_WAIT_L(0); PG8_BAR; PG8_MMA(1, 0, At, B0); PG8_MMA(1, 1, At, B1); PG8_BAR; PG8_SCHED;
.LBB0_643:
	s_add_u32 s24, s22, 0xfffe0080
	s_addc_u32 s25, s23, -1
	s_add_i32 s78, 0, 0x10000
	s_cmp_eq_u32 s83, 4
	s_cselect_b32 s31, s47, s25
	s_cselect_b32 s30, s77, s24
	v_add_u32_e32 v1, s78, v211
	s_cselect_b32 s25, s39, s82
	s_cselect_b32 s24, s80, s81
	s_add_i32 s79, 0, 0x14000
	ds_read_b128 v[132:135], v1
	ds_read_b128 v[136:139], v1 offset:1024
	ds_read_b128 v[140:143], v1 offset:2048
	ds_read_b128 v[144:147], v1 offset:3072
	v_add_u32_e32 v1, s79, v211
	ds_read_b128 v[148:151], v1
	ds_read_b128 v[152:155], v1 offset:1024
	ds_read_b128 v[156:159], v1 offset:2048
	ds_read_b128 v[160:163], v1 offset:3072
	v_lshl_add_u64 v[2:3], s[22:23], 0, v[194:195]
	s_add_i32 m0, s48, 0xc000
	ds_read_b128 v[164:167], v213
	ds_read_b128 v[168:171], v213 offset:1024
	ds_read_b128 v[172:175], v213 offset:2048
	ds_read_b128 v[176:179], v213 offset:3072
	ds_read_b128 v[198:201], v213 offset:4096
	ds_read_b128 v[202:205], v213 offset:5120
	ds_read_b128 v[206:209], v213 offset:6144
	ds_read_b128 v[214:217], v213 offset:7168
	global_load_lds_dwordx4 v[2:3], off
	v_lshl_add_u64 v[2:3], s[22:23], 0, v[196:197]
	s_add_i32 m0, s48, 0xe000
	s_nop 0
	global_load_lds_dwordx4 v[2:3], off
	s_waitcnt vmcnt(8)
	s_waitcnt lgkmcnt(0)
	s_setprio 1
	s_waitcnt lgkmcnt(0)
	s_barrier
	v_mfma_f32_16x16x32_bf16 v[128:131], v[132:135], v[164:167], v[128:131]
	v_mfma_f32_16x16x32_bf16 v[124:127], v[140:143], v[164:167], v[124:127]
	v_mfma_f32_16x16x32_bf16 v[120:123], v[132:135], v[172:175], v[120:123]
	v_mfma_f32_16x16x32_bf16 v[116:119], v[140:143], v[172:175], v[116:119]
	v_mfma_f32_16x16x32_bf16 v[112:115], v[132:135], v[198:201], v[112:115]
	v_mfma_f32_16x16x32_bf16 v[108:111], v[140:143], v[198:201], v[108:111]
	v_mfma_f32_16x16x32_bf16 v[104:107], v[132:135], v[206:209], v[104:107]
	v_mfma_f32_16x16x32_bf16 v[100:103], v[140:143], v[206:209], v[100:103]
	v_mfma_f32_16x16x32_bf16 v[128:131], v[136:139], v[168:171], v[128:131]
	v_mfma_f32_16x16x32_bf16 v[124:127], v[144:147], v[168:171], v[124:127]
	v_mfma_f32_16x16x32_bf16 v[120:123], v[136:139], v[176:179], v[120:123]
	v_mfma_f32_16x16x32_bf16 v[116:119], v[144:147], v[176:179], v[116:119]
	v_mfma_f32_16x16x32_bf16 v[112:115], v[136:139], v[202:205], v[112:115]
	v_mfma_f32_16x16x32_bf16 v[108:111], v[144:147], v[202:205], v[108:111]
	v_mfma_f32_16x16x32_bf16 v[104:107], v[136:139], v[214:217], v[104:107]
	v_mfma_f32_16x16x32_bf16 v[100:103], v[144:147], v[214:217], v[100:103]
	v_mfma_f32_16x16x32_bf16 v[96:99], v[148:151], v[164:167], v[96:99]
	v_mfma_f32_16x16x32_bf16 v[92:95], v[156:159], v[164:167], v[92:95]
	v_mfma_f32_16x16x32_bf16 v[88:91], v[148:151], v[172:175], v[88:91]
	v_mfma_f32_16x16x32_bf16 v[84:87], v[156:159], v[172:175], v[84:87]
	v_mfma_f32_16x16x32_bf16 v[80:83], v[148:151], v[198:201], v[80:83]
	v_mfma_f32_16x16x32_bf16 v[76:79], v[156:159], v[198:201], v[76:79]
	v_mfma_f32_16x16x32_bf16 v[72:75], v[148:151], v[206:209], v[72:75]
	v_mfma_f32_16x16x32_bf16 v[68:71], v[156:159], v[206:209], v[68:71]
	v_mfma_f32_16x16x32_bf16 v[96:99], v[152:155], v[168:171], v[96:99]
	v_mfma_f32_16x16x32_bf16 v[92:95], v[160:163], v[168:171], v[92:95]
	v_mfma_f32_16x16x32_bf16 v[88:91], v[152:155], v[176:179], v[88:91]
	v_mfma_f32_16x16x32_bf16 v[84:87], v[160:163], v[176:179], v[84:87]
	v_mfma_f32_16x16x32_bf16 v[80:83], v[152:155], v[202:205], v[80:83]
	v_mfma_f32_16x16x32_bf16 v[76:79], v[160:163], v[202:205], v[76:79]
	v_mfma_f32_16x16x32_bf16 v[72:75], v[152:155], v[214:217], v[72:75]
	v_mfma_f32_16x16x32_bf16 v[68:71], v[160:163], v[214:217], v[68:71]
	s_barrier
	s_setprio 0
	s_add_i32 s78, s78, s36
	v_lshl_add_u64 v[218:219], s[24:25], 0, v[190:191]
	s_mov_b32 m0, s78
	ds_read_b128 v[164:167], v213 offset:16384
	ds_read_b128 v[168:171], v213 offset:17408
	ds_read_b128 v[172:175], v213 offset:18432
	ds_read_b128 v[176:179], v213 offset:19456
	ds_read_b128 v[198:201], v213 offset:20480
	ds_read_b128 v[202:205], v213 offset:21504
	ds_read_b128 v[206:209], v213 offset:22528
	ds_read_b128 v[214:217], v213 offset:23552
	global_load_lds_dwordx4 v[218:219], off
	s_add_i32 m0, s78, 0x2000
	s_add_u32 s90, s24, 0x20000
	v_lshl_add_u64 v[220:221], s[24:25], 0, v[186:187]
	s_addc_u32 s91, s25, 0
	s_add_i32 s78, s79, s36
	global_load_lds_dwordx4 v[220:221], off
	v_lshl_add_u64 v[2:3], s[90:91], 0, v[190:191]
	s_mov_b32 m0, s78
	v_lshl_add_u64 v[234:235], s[30:31], 0, v[192:193]
	global_load_lds_dwordx4 v[2:3], off
	v_lshl_add_u64 v[2:3], s[90:91], 0, v[186:187]
	s_add_i32 m0, s78, 0x2000
	v_lshl_add_u64 v[236:237], s[30:31], 0, v[188:189]
	global_load_lds_dwordx4 v[2:3], off
	s_mov_b32 m0, s48
	s_nop 0
	global_load_lds_dwordx4 v[234:235], off
	s_mov_b32 m0, s49
	s_nop 0
	global_load_lds_dwordx4 v[236:237], off
	s_waitcnt vmcnt(8)
	s_waitcnt lgkmcnt(0)
	s_setprio 1
	s_waitcnt lgkmcnt(0)
	s_barrier
; #define PG8_STAGE(bufoff, gbase, voff) do { _Pragma("unroll") for (int _i = 0; _i < 2; ++_i) \
;         __builtin_amdgcn_global_load_lds((const unsigned*)((const char*)(gbase) + (voff)[_i]), (PG8_LAS unsigned*)(lds + (bufoff) + ldsw + _i * 8192), 16, 0, 0); } while (0)
; #define PG8_LDA(dst, b, h) do { _Pragma("unroll") for (int m = 0; m < 4; ++m) _Pragma("unroll") for (int k = 0; k < 2; ++k) dst[m][k] = *(const PG8_LAS bf16x8*)(lds + PG8_SA(b, h) + aoff + m * 2048 + k * 1024); } while (0)
; #define PG8_LDB(dst, b, h) do { _Pragma("unroll") for (int n = 0; n < 2; ++n) _Pragma("unroll") for (int k = 0; k < 2; ++k) dst[n][k] = *(const PG8_LAS bf16x8*)(lds + PG8_SB(b, h) + boff + n * 2048 + k * 1024); } while (0)
; #define PG8_MMA(ai, bj, At, Bt) do { __builtin_amdgcn_s_setprio(1); _Pragma("unroll") for (int m = 0; m < 4; ++m) _Pragma("unroll") for (int n = 0; n < 2; ++n) _Pragma("unroll") for (int k = 0; k < 2; ++k) \
;         acc[ai][bj][m][n] = __builtin_amdgcn_mfma_f32_16x16x32_bf16(Bt[n][k], At[m][k], acc[ai][bj][m][n], 0, 0, 0); __builtin_amdgcn_s_setprio(0); } while (0)
; #define PG8_WAIT_V(n) asm volatile("s_waitcnt vmcnt(" #n ")" ::: "memory")
; #define PG8_WAIT_L(n) asm volatile("s_waitcnt lgkmcnt(" #n ")" ::: "memory")
; #define PG8_BAR __builtin_amdgcn_s_barrier()
; #define PG8_SCHED __builtin_amdgcn_sched_barrier(0)
; template <class Epi, class Sched, bool ALIGN_EPI = false, bool SP2 = false>
; __device__ __forceinline__ void gemm_phase(PG8_LAS unsigned char* lds, const Gemm g, const Sched& S, const Epi& E) {
;     ...
;             PG8_WAIT_V(8); PG8_WAIT_L(0); PG8_BAR; PG8_MMA(1, 0, At, B0); PG8_MMA(1, 1, At, B1); PG8_BAR; PG8_SCHED;
;             PG8_LDB(B0, 1, 0); PG8_LDB(B1, 1, 1); PG8_SCHED; PG8_LDA(At, 1, 0); PG8_STAGE(PG8_SA(0, 1), a2 + hstepA, voffA);
;             PG8_WAIT_V(8); PG8_WAIT_L(0); PG8_BAR; PG8_MMA(0, 0, At, B0); PG8_MMA(0, 1, At, B1); PG8_BAR; PG8_SCHED;
	v_mfma_f32_16x16x32_bf16 v[64:67], v[132:135], v[164:167], v[64:67]
	v_mfma_f32_16x16x32_bf16 v[60:63], v[140:143], v[164:167], v[60:63]
	v_mfma_f32_16x16x32_bf16 v[56:59], v[132:135], v[172:175], v[56:59]
	v_mfma_f32_16x16x32_bf16 v[52:55], v[140:143], v[172:175], v[52:55]
	v_mfma_f32_16x16x32_bf16 v[48:51], v[132:135], v[198:201], v[48:51]
	v_mfma_f32_16x16x32_bf16 v[44:47], v[140:143], v[198:201], v[44:47]
	v_mfma_f32_16x16x32_bf16 v[40:43], v[132:135], v[206:209], v[40:43]
	v_mfma_f32_16x16x32_bf16 v[36:39], v[140:143], v[206:209], v[36:39]
	v_mfma_f32_16x16x32_bf16 v[64:67], v[136:139], v[168:171], v[64:67]
	v_mfma_f32_16x16x32_bf16 v[60:63], v[144:147], v[168:171], v[60:63]
	v_mfma_f32_16x16x32_bf16 v[56:59], v[136:139], v[176:179], v[56:59]
	v_mfma_f32_16x16x32_bf16 v[52:55], v[144:147], v[176:179], v[52:55]
	v_mfma_f32_16x16x32_bf16 v[48:51], v[136:139], v[202:205], v[48:51]
	v_mfma_f32_16x16x32_bf16 v[44:47], v[144:147], v[202:205], v[44:47]
	v_mfma_f32_16x16x32_bf16 v[40:43], v[136:139], v[214:217], v[40:43]
	v_mfma_f32_16x16x32_bf16 v[36:39], v[144:147], v[214:217], v[36:39]
	v_mfma_f32_16x16x32_bf16 v[32:35], v[148:151], v[164:167], v[32:35]
	v_mfma_f32_16x16x32_bf16 v[28:31], v[156:159], v[164:167], v[28:31]
	v_mfma_f32_16x16x32_bf16 v[24:27], v[148:151], v[172:175], v[24:27]
	v_mfma_f32_16x16x32_bf16 v[20:23], v[156:159], v[172:175], v[20:23]
	v_mfma_f32_16x16x32_bf16 v[16:19], v[148:151], v[198:201], v[16:19]
	v_mfma_f32_16x16x32_bf16 v[12:15], v[156:159], v[198:201], v[12:15]
	v_mfma_f32_16x16x32_bf16 v[8:11], v[148:151], v[206:209], v[8:11]
	v_mfma_f32_16x16x32_bf16 v[2:5], v[156:159], v[206:209], v[4:7]
	v_mfma_f32_16x16x32_bf16 v[32:35], v[152:155], v[168:171], v[32:35]
	v_mfma_f32_16x16x32_bf16 v[28:31], v[160:163], v[168:171], v[28:31]
	v_mfma_f32_16x16x32_bf16 v[24:27], v[152:155], v[176:179], v[24:27]
	v_mfma_f32_16x16x32_bf16 v[20:23], v[160:163], v[176:179], v[20:23]
	v_mfma_f32_16x16x32_bf16 v[16:19], v[152:155], v[202:205], v[16:19]
	v_mfma_f32_16x16x32_bf16 v[12:15], v[160:163], v[202:205], v[12:15]
	v_mfma_f32_16x16x32_bf16 v[8:11], v[152:155], v[214:217], v[8:11]
	v_mfma_f32_16x16x32_bf16 v[2:5], v[160:163], v[214:217], v[2:5]
	s_barrier
	s_setprio 0
	s_add_i32 s78, 0, 0x18000
	v_add_u32_e32 v1, s78, v211
	s_add_i32 s79, 0, 0x1c000
	ds_read_b128 v[132:135], v1
	ds_read_b128 v[136:139], v1 offset:1024
	ds_read_b128 v[140:143], v1 offset:2048
	ds_read_b128 v[144:147], v1 offset:3072
	v_add_u32_e32 v1, s79, v211
	ds_read_b128 v[148:151], v1
	ds_read_b128 v[152:155], v1 offset:1024
	ds_read_b128 v[156:159], v1 offset:2048
	ds_read_b128 v[160:163], v1 offset:3072
	s_add_u32 s30, s30, 0x20000
	s_addc_u32 s31, s31, 0
	s_mov_b32 m0, s50
	v_lshl_add_u64 v[6:7], s[30:31], 0, v[192:193]
	ds_read_b128 v[164:167], v213 offset:32768
	ds_read_b128 v[168:171], v213 offset:33792
	ds_read_b128 v[172:175], v213 offset:34816
	ds_read_b128 v[176:179], v213 offset:35840
	ds_read_b128 v[198:201], v213 offset:36864
	ds_read_b128 v[202:205], v213 offset:37888
	ds_read_b128 v[206:209], v213 offset:38912
	ds_read_b128 v[214:217], v213 offset:39936
	global_load_lds_dwordx4 v[6:7], off
	v_lshl_add_u64 v[6:7], s[30:31], 0, v[188:189]
	s_mov_b32 m0, s51
	s_nop 0
	global_load_lds_dwordx4 v[6:7], off
	s_waitcnt vmcnt(8)
	s_waitcnt lgkmcnt(0)
	s_setprio 1
	s_waitcnt lgkmcnt(0)
	s_barrier
	v_mfma_f32_16x16x32_bf16 v[128:131], v[132:135], v[164:167], v[128:131]
	v_mfma_f32_16x16x32_bf16 v[124:127], v[140:143], v[164:167], v[124:127]
	v_mfma_f32_16x16x32_bf16 v[120:123], v[132:135], v[172:175], v[120:123]
	v_mfma_f32_16x16x32_bf16 v[116:119], v[140:143], v[172:175], v[116:119]
	v_mfma_f32_16x16x32_bf16 v[112:115], v[132:135], v[198:201], v[112:115]
	v_mfma_f32_16x16x32_bf16 v[108:111], v[140:143], v[198:201], v[108:111]
	v_mfma_f32_16x16x32_bf16 v[104:107], v[132:135], v[206:209], v[104:107]
	v_mfma_f32_16x16x32_bf16 v[100:103], v[140:143], v[206:209], v[100:103]
	v_mfma_f32_16x16x32_bf16 v[128:131], v[136:139], v[168:171], v[128:131]
	v_mfma_f32_16x16x32_bf16 v[124:127], v[144:147], v[168:171], v[124:127]
	v_mfma_f32_16x16x32_bf16 v[120:123], v[136:139], v[176:179], v[120:123]
	v_mfma_f32_16x16x32_bf16 v[116:119], v[144:147], v[176:179], v[116:119]
	v_mfma_f32_16x16x32_bf16 v[112:115], v[136:139], v[202:205], v[112:115]
	v_mfma_f32_16x16x32_bf16 v[108:111], v[144:147], v[202:205], v[108:111]
	v_mfma_f32_16x16x32_bf16 v[104:107], v[136:139], v[214:217], v[104:107]
	v_mfma_f32_16x16x32_bf16 v[100:103], v[144:147], v[214:217], v[100:103]
	v_mfma_f32_16x16x32_bf16 v[96:99], v[148:151], v[164:167], v[96:99]
	v_mfma_f32_16x16x32_bf16 v[92:95], v[156:159], v[164:167], v[92:95]
	v_mfma_f32_16x16x32_bf16 v[88:91], v[148:151], v[172:175], v[88:91]
	v_mfma_f32_16x16x32_bf16 v[84:87], v[156:159], v[172:175], v[84:87]
	v_mfma_f32_16x16x32_bf16 v[80:83], v[148:151], v[198:201], v[80:83]
	v_mfma_f32_16x16x32_bf16 v[76:79], v[156:159], v[198:201], v[76:79]
	v_mfma_f32_16x16x32_bf16 v[72:75], v[148:151], v[206:209], v[72:75]
	v_mfma_f32_16x16x32_bf16 v[68:71], v[156:159], v[206:209], v[68:71]
	v_mfma_f32_16x16x32_bf16 v[96:99], v[152:155], v[168:171], v[96:99]
	v_mfma_f32_16x16x32_bf16 v[92:95], v[160:163], v[168:171], v[92:95]
	v_mfma_f32_16x16x32_bf16 v[88:91], v[152:155], v[176:179], v[88:91]
	v_mfma_f32_16x16x32_bf16 v[84:87], v[160:163], v[176:179], v[84:87]
	v_mfma_f32_16x16x32_bf16 v[80:83], v[152:155], v[202:205], v[80:83]
	v_mfma_f32_16x16x32_bf16 v[76:79], v[160:163], v[202:205], v[76:79]
	v_mfma_f32_16x16x32_bf16 v[72:75], v[152:155], v[214:217], v[72:75]
	v_mfma_f32_16x16x32_bf16 v[68:71], v[160:163], v[214:217], v[68:71]
	s_barrier
; #define PG8_STAGE(bufoff, gbase, voff) do { _Pragma("unroll") for (int _i = 0; _i < 2; ++_i) \
;         __builtin_amdgcn_global_load_lds((const unsigned*)((const char*)(gbase) + (voff)[_i]), (PG8_LAS unsigned*)(lds + (bufoff) + ldsw + _i * 8192), 16, 0, 0); } while (0)
; #define PG8_LDA(dst, b, h) do { _Pragma("unroll") for (int m = 0; m < 4; ++m) _Pragma("unroll") for (int k = 0; k < 2; ++k) dst[m][k] = *(const PG8_LAS bf16x8*)(lds + PG8_SA(b, h) + aoff + m * 2048 + k * 1024); } while (0)
; #define PG8_MMA(ai, bj, At, Bt) do { __builtin_amdgcn_s_setprio(1); _Pragma("unroll") for (int m = 0; m < 4; ++m) _Pragma("unroll") for (int n = 0; n < 2; ++n) _Pragma("unroll") for (int k = 0; k < 2; ++k) \
;         acc[ai][bj][m][n] = __builtin_amdgcn_mfma_f32_16x16x32_bf16(Bt[n][k], At[m][k], acc[ai][bj][m][n], 0, 0, 0); __builtin_amdgcn_s_setprio(0); } while (0)
; #define PG8_WAIT_V(n) asm volatile("s_waitcnt vmcnt(" #n ")" ::: "memory")
; #define PG8_WAIT_L(n) asm volatile("s_waitcnt lgkmcnt(" #n ")" ::: "memory")
; #define PG8_BAR __builtin_amdgcn_s_barrier()
; #define PG8_SCHED __builtin_amdgcn_sched_barrier(0)
; template <class Epi, class Sched, bool ALIGN_EPI = false, bool SP2 = false>
; __device__ __forceinline__ void gemm_phase(PG8_LAS unsigned char* lds, const Gemm g, const Sched& S, const Epi& E) {
;     ...
;             PG8_WAIT_V(8); PG8_WAIT_L(0); PG8_BAR; PG8_MMA(0, 0, At, B0); PG8_MMA(0, 1, At, B1); PG8_BAR; PG8_SCHED;
;             PG8_LDA(At, 1, 1); PG8_STAGE(PG8_SB(1, 0), b3, voffB); PG8_STAGE(PG8_SB(1, 1), b3 + hstepB, voffB); PG8_STAGE(PG8_SA(1, 0), a3, voffA);
;             PG8_WAIT_V(8); PG8_WAIT_L(0); PG8_BAR; PG8_MMA(1, 0, At, B0); PG8_MMA(1, 1, At, B1); PG8_BAR; PG8_SCHED;
;     ...
;         if constexpr (ALIGN_EPI) { if (wr == 0) PG8_BAR; }
	s_setprio 0
	s_add_i32 s30, s78, s36
	v_lshl_add_u64 v[6:7], v[218:219], 0, s[62:63]
	s_mov_b32 m0, s30
	ds_read_b128 v[164:167], v213 offset:49152
	ds_read_b128 v[168:171], v213 offset:50176
	ds_read_b128 v[172:175], v213 offset:51200
	ds_read_b128 v[176:179], v213 offset:52224
	ds_read_b128 v[198:201], v213 offset:53248
	ds_read_b128 v[202:205], v213 offset:54272
	ds_read_b128 v[206:209], v213 offset:55296
	ds_read_b128 v[214:217], v213 offset:56320
	global_load_lds_dwordx4 v[6:7], off
	s_add_i32 m0, s30, 0x2000
	s_add_u32 s24, s24, 0x20080
	v_lshl_add_u64 v[6:7], v[220:221], 0, s[62:63]
	s_addc_u32 s25, s25, 0
	s_add_i32 s30, s79, s36
	global_load_lds_dwordx4 v[6:7], off
	v_lshl_add_u64 v[6:7], s[24:25], 0, v[190:191]
	s_mov_b32 m0, s30
	s_nop 0
	global_load_lds_dwordx4 v[6:7], off
	v_lshl_add_u64 v[6:7], s[24:25], 0, v[186:187]
	s_add_i32 m0, s30, 0x2000
	s_nop 0
	global_load_lds_dwordx4 v[6:7], off
	v_lshl_add_u64 v[6:7], v[234:235], 0, s[62:63]
	s_mov_b32 m0, s60
	s_nop 0
	global_load_lds_dwordx4 v[6:7], off
	v_lshl_add_u64 v[6:7], v[236:237], 0, s[62:63]
	s_mov_b32 m0, s61
	s_nop 0
	global_load_lds_dwordx4 v[6:7], off
	s_waitcnt vmcnt(8)
	s_waitcnt lgkmcnt(0)
	s_setprio 1
	s_waitcnt lgkmcnt(0)
	s_barrier
	v_mfma_f32_16x16x32_bf16 v[64:67], v[132:135], v[164:167], v[64:67]
	v_mfma_f32_16x16x32_bf16 v[60:63], v[140:143], v[164:167], v[60:63]
	v_mfma_f32_16x16x32_bf16 v[56:59], v[132:135], v[172:175], v[56:59]
	v_mfma_f32_16x16x32_bf16 v[52:55], v[140:143], v[172:175], v[52:55]
	v_mfma_f32_16x16x32_bf16 v[48:51], v[132:135], v[198:201], v[48:51]
	v_mfma_f32_16x16x32_bf16 v[44:47], v[140:143], v[198:201], v[44:47]
	v_mfma_f32_16x16x32_bf16 v[40:43], v[132:135], v[206:209], v[40:43]
	v_mfma_f32_16x16x32_bf16 v[36:39], v[140:143], v[206:209], v[36:39]
	v_mfma_f32_16x16x32_bf16 v[64:67], v[136:139], v[168:171], v[64:67]
	v_mfma_f32_16x16x32_bf16 v[60:63], v[144:147], v[168:171], v[60:63]
	v_mfma_f32_16x16x32_bf16 v[56:59], v[136:139], v[176:179], v[56:59]
	v_mfma_f32_16x16x32_bf16 v[52:55], v[144:147], v[176:179], v[52:55]
	v_mfma_f32_16x16x32_bf16 v[48:51], v[136:139], v[202:205], v[48:51]
	v_mfma_f32_16x16x32_bf16 v[44:47], v[144:147], v[202:205], v[44:47]
	v_mfma_f32_16x16x32_bf16 v[40:43], v[136:139], v[214:217], v[40:43]
	v_mfma_f32_16x16x32_bf16 v[36:39], v[144:147], v[214:217], v[36:39]
	v_mfma_f32_16x16x32_bf16 v[32:35], v[148:151], v[164:167], v[32:35]
	v_mfma_f32_16x16x32_bf16 v[28:31], v[156:159], v[164:167], v[28:31]
	v_mfma_f32_16x16x32_bf16 v[24:27], v[148:151], v[172:175], v[24:27]
	v_mfma_f32_16x16x32_bf16 v[20:23], v[156:159], v[172:175], v[20:23]
	v_mfma_f32_16x16x32_bf16 v[16:19], v[148:151], v[198:201], v[16:19]
	v_mfma_f32_16x16x32_bf16 v[12:15], v[156:159], v[198:201], v[12:15]
	v_mfma_f32_16x16x32_bf16 v[6:9], v[148:151], v[206:209], v[8:11]
	v_mfma_f32_16x16x32_bf16 v[2:5], v[156:159], v[206:209], v[2:5]
	v_mfma_f32_16x16x32_bf16 v[32:35], v[152:155], v[168:171], v[32:35]
	v_mfma_f32_16x16x32_bf16 v[28:31], v[160:163], v[168:171], v[28:31]
	v_mfma_f32_16x16x32_bf16 v[24:27], v[152:155], v[176:179], v[24:27]
	v_mfma_f32_16x16x32_bf16 v[20:23], v[160:163], v[176:179], v[20:23]
	v_mfma_f32_16x16x32_bf16 v[16:19], v[152:155], v[202:205], v[16:19]
	v_mfma_f32_16x16x32_bf16 v[12:15], v[160:163], v[202:205], v[12:15]
	v_mfma_f32_16x16x32_bf16 v[8:11], v[152:155], v[214:217], v[6:9]
	v_mfma_f32_16x16x32_bf16 v[4:7], v[160:163], v[214:217], v[2:5]
	s_barrier
	s_setprio 0
	s_add_i32 s83, s83, 2
	s_add_u32 s22, s22, 0x100
	s_addc_u32 s23, s23, 0
	s_add_u32 s81, s81, 0x100
	s_addc_u32 s82, s82, 0
	s_cmp_gt_u32 s83, 5
	s_cbranch_scc0 .LBB0_643
	s_and_b64 vcc, exec, s[44:45]
	s_cbranch_vccz .LBB0_646
	s_barrier

; #define PG8_STAGE(bufoff, gbase, voff) do { _Pragma("unroll") for (int _i = 0; _i < 2; ++_i) \
;         __builtin_amdgcn_global_load_lds((const unsigned*)((const char*)(gbase) + (voff)[_i]), (PG8_LAS unsigned*)(lds + (bufoff) + ldsw + _i * 8192), 16, 0, 0); } while (0)
; #define PG8_LDA(dst, b, h) do { _Pragma("unroll") for (int m = 0; m < 4; ++m) _Pragma("unroll") for (int k = 0; k < 2; ++k) dst[m][k] = *(const PG8_LAS bf16x8*)(lds + PG8_SA(b, h) + aoff + m * 2048 + k * 1024); } while (0)
; #define PG8_LDB(dst, b, h) do { _Pragma("unroll") for (int n = 0; n < 2; ++n) _Pragma("unroll") for (int k = 0; k < 2; ++k) dst[n][k] = *(const PG8_LAS bf16x8*)(lds + PG8_SB(b, h) + boff + n * 2048 + k * 1024); } while (0)
; #define PG8_MMA(ai, bj, At, Bt) do { __builtin_amdgcn_s_setprio(1); _Pragma("unroll") for (int m = 0; m < 4; ++m) _Pragma("unroll") for (int n = 0; n < 2; ++n) _Pragma("unroll") for (int k = 0; k < 2; ++k) \
;         acc[ai][bj][m][n] = __builtin_amdgcn_mfma_f32_16x16x32_bf16(Bt[n][k], At[m][k], acc[ai][bj][m][n], 0, 0, 0); __builtin_amdgcn_s_setprio(0); } while (0)
; #define PG8_WAIT_V(n) asm volatile("s_waitcnt vmcnt(" #n ")" ::: "memory")
; #define PG8_BAR __builtin_amdgcn_s_barrier()
; template <class Epi, class Sched, bool ALIGN_EPI = false, bool SP2 = false>
; __device__ __forceinline__ void gemm_phase(PG8_LAS unsigned char* lds, const Gemm g, const Sched& S, const Epi& E) {
;     ...
;         for (int t = 0; t < nt; t += 2) {
;             const bool last = (t == nt - 2);
;             const char* a1 = cA + (size_t)(t + 1) * kstep;
;             const char* a2 = last ? nA : cA + (size_t)(t + 2) * kstep; const char* b2 = last ? nB : cB + (size_t)(t + 2) * kstep;
;             const char* a3 = a2 + kstep; const char* b3 = b2 + kstep;
;             if (last && has_next) S.a_ready(nxt);
;             if constexpr (SP2) {
;             PG8_LDB(B0, 0, 0); PG8_LDB(B1, 0, 1); PG8_SCHED; PG8_LDA(At, 0, 0); PG8_STAGE(PG8_SA(1, 1), a1 + hstepA, voffA);
;             PG8_WAIT_V(8); PG8_WAIT_L(0); PG8_BAR; PG8_MMA(0, 0, At, B0); PG8_MMA(0, 1, At, B1); PG8_BAR; PG8_SCHED;
;             PG8_LDA(At, 0, 1); PG8_STAGE(PG8_SB(0, 0), b2, voffB); PG8_STAGE(PG8_SB(0, 1), b2 + hstepB, voffB); PG8_STAGE(PG8_SA(0, 0), a2, voffA);
;             PG8_WAIT_V(8); PG8_WAIT_L(0); PG8_BAR; PG8_MMA(1, 0, At, B0); PG8_MMA(1, 1, At, B1); PG8_BAR; PG8_SCHED;
.LBB0_727:
	s_add_u32 s24, s60, 0xfffc0080
	s_addc_u32 s25, s61, -1
	s_add_i32 s77, 0, 0x10000
	s_cmp_eq_u32 s76, 12
	s_cselect_b32 s35, s31, s25
	s_cselect_b32 s34, vcc_lo, s24
	s_cselect_b32 s25, s1, s71
	s_cselect_b32 s24, vcc_hi, s70
	s_add_i32 s4, 0, 0x14000
	v_add_u32_e32 v164, s77, v147
	v_add_u32_e32 v186, s4, v147
	ds_read_b128 v[130:133], v164
	ds_read_b128 v[134:137], v164 offset:1024
	ds_read_b128 v[160:163], v164 offset:2048
	ds_read_b128 v[164:167], v164 offset:3072
	ds_read_b128 v[168:171], v186
	ds_read_b128 v[172:175], v186 offset:1024
	ds_read_b128 v[176:179], v186 offset:2048
	ds_read_b128 v[186:189], v186 offset:3072
	v_lshl_add_u64 v[206:207], s[60:61], 0, v[156:157]
	s_add_i32 m0, s89, 0xc000
	ds_read_b128 v[190:193], v209
	ds_read_b128 v[194:197], v209 offset:1024
	ds_read_b128 v[198:201], v209 offset:2048
	ds_read_b128 v[202:205], v209 offset:3072
	ds_read_b128 v[210:213], v209 offset:4096
	ds_read_b128 v[214:217], v209 offset:5120
	ds_read_b128 v[218:221], v209 offset:6144
	ds_read_b128 v[234:237], v209 offset:7168
	global_load_lds_dwordx4 v[206:207], off
	v_lshl_add_u64 v[206:207], s[60:61], 0, v[158:159]
	s_add_i32 m0, s89, 0xe000
	s_nop 0
	global_load_lds_dwordx4 v[206:207], off
	s_waitcnt vmcnt(8)
	s_waitcnt lgkmcnt(0)
	s_setprio 1
	s_waitcnt lgkmcnt(0)
	s_barrier
	v_mfma_f32_16x16x32_bf16 v[126:129], v[130:133], v[190:193], v[126:129]
	v_mfma_f32_16x16x32_bf16 v[122:125], v[160:163], v[190:193], v[122:125]
	v_mfma_f32_16x16x32_bf16 v[110:113], v[130:133], v[198:201], v[110:113]
	v_mfma_f32_16x16x32_bf16 v[106:109], v[160:163], v[198:201], v[106:109]
	v_mfma_f32_16x16x32_bf16 v[94:97], v[130:133], v[210:213], v[94:97]
	v_mfma_f32_16x16x32_bf16 v[90:93], v[160:163], v[210:213], v[90:93]
	v_mfma_f32_16x16x32_bf16 v[78:81], v[130:133], v[218:221], v[78:81]
	v_mfma_f32_16x16x32_bf16 v[74:77], v[160:163], v[218:221], v[74:77]
	v_mfma_f32_16x16x32_bf16 v[126:129], v[134:137], v[194:197], v[126:129]
	v_mfma_f32_16x16x32_bf16 v[122:125], v[164:167], v[194:197], v[122:125]
	v_mfma_f32_16x16x32_bf16 v[110:113], v[134:137], v[202:205], v[110:113]
	v_mfma_f32_16x16x32_bf16 v[106:109], v[164:167], v[202:205], v[106:109]
	v_mfma_f32_16x16x32_bf16 v[94:97], v[134:137], v[214:217], v[94:97]
	v_mfma_f32_16x16x32_bf16 v[90:93], v[164:167], v[214:217], v[90:93]
	v_mfma_f32_16x16x32_bf16 v[78:81], v[134:137], v[234:237], v[78:81]
	v_mfma_f32_16x16x32_bf16 v[74:77], v[164:167], v[234:237], v[74:77]
	v_mfma_f32_16x16x32_bf16 v[118:121], v[168:171], v[190:193], v[118:121]
	v_mfma_f32_16x16x32_bf16 v[114:117], v[176:179], v[190:193], v[114:117]
	v_mfma_f32_16x16x32_bf16 v[102:105], v[168:171], v[198:201], v[102:105]
	v_mfma_f32_16x16x32_bf16 v[98:101], v[176:179], v[198:201], v[98:101]
	v_mfma_f32_16x16x32_bf16 v[86:89], v[168:171], v[210:213], v[86:89]
	v_mfma_f32_16x16x32_bf16 v[82:85], v[176:179], v[210:213], v[82:85]
	v_mfma_f32_16x16x32_bf16 v[70:73], v[168:171], v[218:221], v[70:73]
	v_mfma_f32_16x16x32_bf16 v[66:69], v[176:179], v[218:221], v[66:69]
	v_mfma_f32_16x16x32_bf16 v[118:121], v[172:175], v[194:197], v[118:121]
	v_mfma_f32_16x16x32_bf16 v[114:117], v[186:189], v[194:197], v[114:117]
	v_mfma_f32_16x16x32_bf16 v[102:105], v[172:175], v[202:205], v[102:105]
	v_mfma_f32_16x16x32_bf16 v[98:101], v[186:189], v[202:205], v[98:101]
	v_mfma_f32_16x16x32_bf16 v[86:89], v[172:175], v[214:217], v[86:89]
	v_mfma_f32_16x16x32_bf16 v[82:85], v[186:189], v[214:217], v[82:85]
	v_mfma_f32_16x16x32_bf16 v[70:73], v[172:175], v[234:237], v[70:73]
	v_mfma_f32_16x16x32_bf16 v[66:69], v[186:189], v[234:237], v[66:69]
	s_barrier
	s_setprio 0
	s_add_i32 s5, s77, s36
	v_lshl_add_u64 v[206:207], s[24:25], 0, v[142:143]
	s_mov_b32 m0, s5
	ds_read_b128 v[190:193], v209 offset:16384
	ds_read_b128 v[194:197], v209 offset:17408
	ds_read_b128 v[198:201], v209 offset:18432
	ds_read_b128 v[202:205], v209 offset:19456
	ds_read_b128 v[210:213], v209 offset:20480
	ds_read_b128 v[214:217], v209 offset:21504
	ds_read_b128 v[218:221], v209 offset:22528
	ds_read_b128 v[234:237], v209 offset:23552
	global_load_lds_dwordx4 v[206:207], off
	s_add_i32 m0, s5, 0x2000
	s_add_u32 s78, s24, 0x40000
	v_lshl_add_u64 v[238:239], s[24:25], 0, v[138:139]
	s_addc_u32 s79, s25, 0
	s_add_i32 s4, s4, s36
	global_load_lds_dwordx4 v[238:239], off
	v_lshl_add_u64 v[240:241], s[78:79], 0, v[142:143]
	s_mov_b32 m0, s4
	v_lshl_add_u64 v[242:243], s[34:35], 0, v[140:141]
	global_load_lds_dwordx4 v[240:241], off
	v_lshl_add_u64 v[240:241], s[78:79], 0, v[138:139]
	s_add_i32 m0, s4, 0x2000
	s_nop 0
	global_load_lds_dwordx4 v[240:241], off
	v_lshl_add_u64 v[240:241], s[34:35], 0, v[144:145]
	s_mov_b32 m0, s89
	s_nop 0
	global_load_lds_dwordx4 v[240:241], off
	s_mov_b32 m0, s90
	s_nop 0
	global_load_lds_dwordx4 v[242:243], off
	s_waitcnt vmcnt(8)
	s_waitcnt lgkmcnt(0)
	s_setprio 1
	s_waitcnt lgkmcnt(0)
	s_barrier
; #define PG8_STAGE(bufoff, gbase, voff) do { _Pragma("unroll") for (int _i = 0; _i < 2; ++_i) \
;         __builtin_amdgcn_global_load_lds((const unsigned*)((const char*)(gbase) + (voff)[_i]), (PG8_LAS unsigned*)(lds + (bufoff) + ldsw + _i * 8192), 16, 0, 0); } while (0)
; #define PG8_LDA(dst, b, h) do { _Pragma("unroll") for (int m = 0; m < 4; ++m) _Pragma("unroll") for (int k = 0; k < 2; ++k) dst[m][k] = *(const PG8_LAS bf16x8*)(lds + PG8_SA(b, h) + aoff + m * 2048 + k * 1024); } while (0)
; #define PG8_LDB(dst, b, h) do { _Pragma("unroll") for (int n = 0; n < 2; ++n) _Pragma("unroll") for (int k = 0; k < 2; ++k) dst[n][k] = *(const PG8_LAS bf16x8*)(lds + PG8_SB(b, h) + boff + n * 2048 + k * 1024); } while (0)
; #define PG8_MMA(ai, bj, At, Bt) do { __builtin_amdgcn_s_setprio(1); _Pragma("unroll") for (int m = 0; m < 4; ++m) _Pragma("unroll") for (int n = 0; n < 2; ++n) _Pragma("unroll") for (int k = 0; k < 2; ++k) \
;         acc[ai][bj][m][n] = __builtin_amdgcn_mfma_f32_16x16x32_bf16(Bt[n][k], At[m][k], acc[ai][bj][m][n], 0, 0, 0); __builtin_amdgcn_s_setprio(0); } while (0)
; #define PG8_WAIT_V(n) asm volatile("s_waitcnt vmcnt(" #n ")" ::: "memory")
; #define PG8_WAIT_L(n) asm volatile("s_waitcnt lgkmcnt(" #n ")" ::: "memory")
; #define PG8_BAR __builtin_amdgcn_s_barrier()
; #define PG8_SCHED __builtin_amdgcn_sched_barrier(0)
; template <class Epi, class Sched, bool ALIGN_EPI = false, bool SP2 = false>
; __device__ __forceinline__ void gemm_phase(PG8_LAS unsigned char* lds, const Gemm g, const Sched& S, const Epi& E) {
;     ...
;             PG8_WAIT_V(8); PG8_WAIT_L(0); PG8_BAR; PG8_MMA(1, 0, At, B0); PG8_MMA(1, 1, At, B1); PG8_BAR; PG8_SCHED;
;             PG8_LDB(B0, 1, 0); PG8_LDB(B1, 1, 1); PG8_SCHED; PG8_LDA(At, 1, 0); PG8_STAGE(PG8_SA(0, 1), a2 + hstepA, voffA);
;             PG8_WAIT_V(8); PG8_WAIT_L(0); PG8_BAR; PG8_MMA(0, 0, At, B0); PG8_MMA(0, 1, At, B1); PG8_BAR; PG8_SCHED;
	v_mfma_f32_16x16x32_bf16 v[62:65], v[130:133], v[190:193], v[62:65]
	v_mfma_f32_16x16x32_bf16 v[58:61], v[160:163], v[190:193], v[58:61]
	v_mfma_f32_16x16x32_bf16 v[46:49], v[130:133], v[198:201], v[46:49]
	v_mfma_f32_16x16x32_bf16 v[42:45], v[160:163], v[198:201], v[42:45]
	v_mfma_f32_16x16x32_bf16 v[30:33], v[130:133], v[210:213], v[30:33]
	v_mfma_f32_16x16x32_bf16 v[26:29], v[160:163], v[210:213], v[26:29]
	v_mfma_f32_16x16x32_bf16 v[14:17], v[130:133], v[218:221], v[14:17]
	v_mfma_f32_16x16x32_bf16 v[10:13], v[160:163], v[218:221], v[10:13]
	v_mfma_f32_16x16x32_bf16 v[62:65], v[134:137], v[194:197], v[62:65]
	v_mfma_f32_16x16x32_bf16 v[58:61], v[164:167], v[194:197], v[58:61]
	v_mfma_f32_16x16x32_bf16 v[46:49], v[134:137], v[202:205], v[46:49]
	v_mfma_f32_16x16x32_bf16 v[42:45], v[164:167], v[202:205], v[42:45]
	v_mfma_f32_16x16x32_bf16 v[30:33], v[134:137], v[214:217], v[30:33]
	v_mfma_f32_16x16x32_bf16 v[26:29], v[164:167], v[214:217], v[26:29]
	v_mfma_f32_16x16x32_bf16 v[14:17], v[134:137], v[234:237], v[14:17]
	v_mfma_f32_16x16x32_bf16 v[10:13], v[164:167], v[234:237], v[10:13]
	v_mfma_f32_16x16x32_bf16 v[54:57], v[168:171], v[190:193], v[54:57]
	v_mfma_f32_16x16x32_bf16 v[50:53], v[176:179], v[190:193], v[50:53]
	v_mfma_f32_16x16x32_bf16 v[38:41], v[168:171], v[198:201], v[38:41]
	v_mfma_f32_16x16x32_bf16 v[34:37], v[176:179], v[198:201], v[34:37]
	v_mfma_f32_16x16x32_bf16 v[22:25], v[168:171], v[210:213], v[22:25]
	v_mfma_f32_16x16x32_bf16 v[18:21], v[176:179], v[210:213], v[18:21]
	v_mfma_f32_16x16x32_bf16 v[6:9], v[168:171], v[218:221], v[6:9]
	v_mfma_f32_16x16x32_bf16 v[2:5], v[176:179], v[218:221], v[2:5]
	v_mfma_f32_16x16x32_bf16 v[54:57], v[172:175], v[194:197], v[54:57]
	v_mfma_f32_16x16x32_bf16 v[50:53], v[186:189], v[194:197], v[50:53]
	v_mfma_f32_16x16x32_bf16 v[38:41], v[172:175], v[202:205], v[38:41]
	v_mfma_f32_16x16x32_bf16 v[34:37], v[186:189], v[202:205], v[34:37]
	v_mfma_f32_16x16x32_bf16 v[22:25], v[172:175], v[214:217], v[22:25]
	v_mfma_f32_16x16x32_bf16 v[18:21], v[186:189], v[214:217], v[18:21]
	v_mfma_f32_16x16x32_bf16 v[6:9], v[172:175], v[234:237], v[6:9]
	v_mfma_f32_16x16x32_bf16 v[2:5], v[186:189], v[234:237], v[2:5]
	s_barrier
	s_setprio 0
	s_add_i32 s4, 0, 0x18000
	s_add_i32 s5, 0, 0x1c000
	v_add_u32_e32 v164, s4, v147
	v_add_u32_e32 v186, s5, v147
	ds_read_b128 v[130:133], v164
	ds_read_b128 v[134:137], v164 offset:1024
	ds_read_b128 v[160:163], v164 offset:2048
	ds_read_b128 v[164:167], v164 offset:3072
	ds_read_b128 v[168:171], v186
	ds_read_b128 v[172:175], v186 offset:1024
	ds_read_b128 v[176:179], v186 offset:2048
	ds_read_b128 v[186:189], v186 offset:3072
	s_add_u32 s34, s34, 0x40000
	s_addc_u32 s35, s35, 0
	s_mov_b32 m0, s91
	v_lshl_add_u64 v[244:245], s[34:35], 0, v[144:145]
	ds_read_b128 v[190:193], v209 offset:32768
	ds_read_b128 v[194:197], v209 offset:33792
	ds_read_b128 v[198:201], v209 offset:34816
	ds_read_b128 v[202:205], v209 offset:35840
	ds_read_b128 v[210:213], v209 offset:36864
	ds_read_b128 v[214:217], v209 offset:37888
	ds_read_b128 v[218:221], v209 offset:38912
	ds_read_b128 v[234:237], v209 offset:39936
	global_load_lds_dwordx4 v[244:245], off
	v_lshl_add_u64 v[244:245], s[34:35], 0, v[140:141]
	s_mov_b32 m0, s92
	s_nop 0
	global_load_lds_dwordx4 v[244:245], off
	s_waitcnt vmcnt(8)
	s_waitcnt lgkmcnt(0)
	s_setprio 1
	s_waitcnt lgkmcnt(0)
	s_barrier
	v_mfma_f32_16x16x32_bf16 v[126:129], v[130:133], v[190:193], v[126:129]
	v_mfma_f32_16x16x32_bf16 v[122:125], v[160:163], v[190:193], v[122:125]
	v_mfma_f32_16x16x32_bf16 v[110:113], v[130:133], v[198:201], v[110:113]
	v_mfma_f32_16x16x32_bf16 v[106:109], v[160:163], v[198:201], v[106:109]
	v_mfma_f32_16x16x32_bf16 v[94:97], v[130:133], v[210:213], v[94:97]
	v_mfma_f32_16x16x32_bf16 v[90:93], v[160:163], v[210:213], v[90:93]
	v_mfma_f32_16x16x32_bf16 v[78:81], v[130:133], v[218:221], v[78:81]
	v_mfma_f32_16x16x32_bf16 v[74:77], v[160:163], v[218:221], v[74:77]
	v_mfma_f32_16x16x32_bf16 v[126:129], v[134:137], v[194:197], v[126:129]
	v_mfma_f32_16x16x32_bf16 v[122:125], v[164:167], v[194:197], v[122:125]
	v_mfma_f32_16x16x32_bf16 v[110:113], v[134:137], v[202:205], v[110:113]
	v_mfma_f32_16x16x32_bf16 v[106:109], v[164:167], v[202:205], v[106:109]
	v_mfma_f32_16x16x32_bf16 v[94:97], v[134:137], v[214:217], v[94:97]
	v_mfma_f32_16x16x32_bf16 v[90:93], v[164:167], v[214:217], v[90:93]
	v_mfma_f32_16x16x32_bf16 v[78:81], v[134:137], v[234:237], v[78:81]
	v_mfma_f32_16x16x32_bf16 v[74:77], v[164:167], v[234:237], v[74:77]
	v_mfma_f32_16x16x32_bf16 v[118:121], v[168:171], v[190:193], v[118:121]
	v_mfma_f32_16x16x32_bf16 v[114:117], v[176:179], v[190:193], v[114:117]
	v_mfma_f32_16x16x32_bf16 v[102:105], v[168:171], v[198:201], v[102:105]
	v_mfma_f32_16x16x32_bf16 v[98:101], v[176:179], v[198:201], v[98:101]
	v_mfma_f32_16x16x32_bf16 v[86:89], v[168:171], v[210:213], v[86:89]
	v_mfma_f32_16x16x32_bf16 v[82:85], v[176:179], v[210:213], v[82:85]
	v_mfma_f32_16x16x32_bf16 v[70:73], v[168:171], v[218:221], v[70:73]
	v_mfma_f32_16x16x32_bf16 v[66:69], v[176:179], v[218:221], v[66:69]
	v_mfma_f32_16x16x32_bf16 v[118:121], v[172:175], v[194:197], v[118:121]
	v_mfma_f32_16x16x32_bf16 v[114:117], v[186:189], v[194:197], v[114:117]
	v_mfma_f32_16x16x32_bf16 v[102:105], v[172:175], v[202:205], v[102:105]
	v_mfma_f32_16x16x32_bf16 v[98:101], v[186:189], v[202:205], v[98:101]
	v_mfma_f32_16x16x32_bf16 v[86:89], v[172:175], v[214:217], v[86:89]
	v_mfma_f32_16x16x32_bf16 v[82:85], v[186:189], v[214:217], v[82:85]
	v_mfma_f32_16x16x32_bf16 v[70:73], v[172:175], v[234:237], v[70:73]
	v_mfma_f32_16x16x32_bf16 v[66:69], v[186:189], v[234:237], v[66:69]
	s_barrier
; #define PG8_STAGE(bufoff, gbase, voff) do { _Pragma("unroll") for (int _i = 0; _i < 2; ++_i) \
;         __builtin_amdgcn_global_load_lds((const unsigned*)((const char*)(gbase) + (voff)[_i]), (PG8_LAS unsigned*)(lds + (bufoff) + ldsw + _i * 8192), 16, 0, 0); } while (0)
; #define PG8_LDA(dst, b, h) do { _Pragma("unroll") for (int m = 0; m < 4; ++m) _Pragma("unroll") for (int k = 0; k < 2; ++k) dst[m][k] = *(const PG8_LAS bf16x8*)(lds + PG8_SA(b, h) + aoff + m * 2048 + k * 1024); } while (0)
; #define PG8_MMA(ai, bj, At, Bt) do { __builtin_amdgcn_s_setprio(1); _Pragma("unroll") for (int m = 0; m < 4; ++m) _Pragma("unroll") for (int n = 0; n < 2; ++n) _Pragma("unroll") for (int k = 0; k < 2; ++k) \
;         acc[ai][bj][m][n] = __builtin_amdgcn_mfma_f32_16x16x32_bf16(Bt[n][k], At[m][k], acc[ai][bj][m][n], 0, 0, 0); __builtin_amdgcn_s_setprio(0); } while (0)
; #define PG8_WAIT_V(n) asm volatile("s_waitcnt vmcnt(" #n ")" ::: "memory")
; #define PG8_WAIT_L(n) asm volatile("s_waitcnt lgkmcnt(" #n ")" ::: "memory")
; #define PG8_BAR __builtin_amdgcn_s_barrier()
; #define PG8_SCHED __builtin_amdgcn_sched_barrier(0)
; template <class Epi, class Sched, bool ALIGN_EPI = false, bool SP2 = false>
; __device__ __forceinline__ void gemm_phase(PG8_LAS unsigned char* lds, const Gemm g, const Sched& S, const Epi& E) {
;     ...
;             PG8_WAIT_V(8); PG8_WAIT_L(0); PG8_BAR; PG8_MMA(0, 0, At, B0); PG8_MMA(0, 1, At, B1); PG8_BAR; PG8_SCHED;
;             PG8_LDA(At, 1, 1); PG8_STAGE(PG8_SB(1, 0), b3, voffB); PG8_STAGE(PG8_SB(1, 1), b3 + hstepB, voffB); PG8_STAGE(PG8_SA(1, 0), a3, voffA);
;             PG8_WAIT_V(8); PG8_WAIT_L(0); PG8_BAR; PG8_MMA(1, 0, At, B0); PG8_MMA(1, 1, At, B1); PG8_BAR; PG8_SCHED;
;     ...
;         if constexpr (ALIGN_EPI) { if (wr == 0) PG8_BAR; }
	s_setprio 0
	s_add_i32 s4, s4, s36
	v_lshl_add_u64 v[206:207], v[206:207], 0, s[62:63]
	s_mov_b32 m0, s4
	ds_read_b128 v[190:193], v209 offset:49152
	ds_read_b128 v[194:197], v209 offset:50176
	ds_read_b128 v[198:201], v209 offset:51200
	ds_read_b128 v[202:205], v209 offset:52224
	ds_read_b128 v[210:213], v209 offset:53248
	ds_read_b128 v[214:217], v209 offset:54272
	ds_read_b128 v[218:221], v209 offset:55296
	ds_read_b128 v[234:237], v209 offset:56320
	global_load_lds_dwordx4 v[206:207], off
	s_add_i32 m0, s4, 0x2000
	s_add_u32 s24, s24, 0x40080
	v_lshl_add_u64 v[206:207], v[238:239], 0, s[62:63]
	s_addc_u32 s25, s25, 0
	s_add_i32 s4, s5, s36
	global_load_lds_dwordx4 v[206:207], off
	v_lshl_add_u64 v[206:207], s[24:25], 0, v[142:143]
	s_mov_b32 m0, s4
	s_nop 0
	global_load_lds_dwordx4 v[206:207], off
	v_lshl_add_u64 v[206:207], s[24:25], 0, v[138:139]
	s_add_i32 m0, s4, 0x2000
	s_nop 0
	global_load_lds_dwordx4 v[206:207], off
	v_lshl_add_u64 v[206:207], v[240:241], 0, s[62:63]
	s_mov_b32 m0, s97
	s_nop 0
	global_load_lds_dwordx4 v[206:207], off
	v_lshl_add_u64 v[206:207], v[242:243], 0, s[62:63]
	s_mov_b32 m0, s80
	s_nop 0
	global_load_lds_dwordx4 v[206:207], off
	s_waitcnt vmcnt(8)
	s_waitcnt lgkmcnt(0)
	s_setprio 1
	s_waitcnt lgkmcnt(0)
	s_barrier
	v_mfma_f32_16x16x32_bf16 v[62:65], v[130:133], v[190:193], v[62:65]
	v_mfma_f32_16x16x32_bf16 v[58:61], v[160:163], v[190:193], v[58:61]
	v_mfma_f32_16x16x32_bf16 v[46:49], v[130:133], v[198:201], v[46:49]
	v_mfma_f32_16x16x32_bf16 v[42:45], v[160:163], v[198:201], v[42:45]
	v_mfma_f32_16x16x32_bf16 v[30:33], v[130:133], v[210:213], v[30:33]
	v_mfma_f32_16x16x32_bf16 v[26:29], v[160:163], v[210:213], v[26:29]
	v_mfma_f32_16x16x32_bf16 v[14:17], v[130:133], v[218:221], v[14:17]
	v_mfma_f32_16x16x32_bf16 v[10:13], v[160:163], v[218:221], v[10:13]
	v_mfma_f32_16x16x32_bf16 v[62:65], v[134:137], v[194:197], v[62:65]
	v_mfma_f32_16x16x32_bf16 v[58:61], v[164:167], v[194:197], v[58:61]
	v_mfma_f32_16x16x32_bf16 v[46:49], v[134:137], v[202:205], v[46:49]
	v_mfma_f32_16x16x32_bf16 v[42:45], v[164:167], v[202:205], v[42:45]
	v_mfma_f32_16x16x32_bf16 v[30:33], v[134:137], v[214:217], v[30:33]
	v_mfma_f32_16x16x32_bf16 v[26:29], v[164:167], v[214:217], v[26:29]
	v_mfma_f32_16x16x32_bf16 v[14:17], v[134:137], v[234:237], v[14:17]
	v_mfma_f32_16x16x32_bf16 v[10:13], v[164:167], v[234:237], v[10:13]
	v_mfma_f32_16x16x32_bf16 v[54:57], v[168:171], v[190:193], v[54:57]
	v_mfma_f32_16x16x32_bf16 v[50:53], v[176:179], v[190:193], v[50:53]
	v_mfma_f32_16x16x32_bf16 v[38:41], v[168:171], v[198:201], v[38:41]
	v_mfma_f32_16x16x32_bf16 v[34:37], v[176:179], v[198:201], v[34:37]
	v_mfma_f32_16x16x32_bf16 v[22:25], v[168:171], v[210:213], v[22:25]
	v_mfma_f32_16x16x32_bf16 v[18:21], v[176:179], v[210:213], v[18:21]
	v_mfma_f32_16x16x32_bf16 v[6:9], v[168:171], v[218:221], v[6:9]
	v_mfma_f32_16x16x32_bf16 v[2:5], v[176:179], v[218:221], v[2:5]
	v_mfma_f32_16x16x32_bf16 v[54:57], v[172:175], v[194:197], v[54:57]
	v_mfma_f32_16x16x32_bf16 v[50:53], v[186:189], v[194:197], v[50:53]
	v_mfma_f32_16x16x32_bf16 v[38:41], v[172:175], v[202:205], v[38:41]
	v_mfma_f32_16x16x32_bf16 v[34:37], v[186:189], v[202:205], v[34:37]
	v_mfma_f32_16x16x32_bf16 v[22:25], v[172:175], v[214:217], v[22:25]
	v_mfma_f32_16x16x32_bf16 v[18:21], v[186:189], v[214:217], v[18:21]
	v_mfma_f32_16x16x32_bf16 v[6:9], v[172:175], v[234:237], v[6:9]
	v_mfma_f32_16x16x32_bf16 v[2:5], v[186:189], v[234:237], v[2:5]
	s_barrier
	s_setprio 0
	s_add_i32 s76, s76, 2
	s_add_u32 s60, s60, 0x100
	s_addc_u32 s61, s61, 0
	s_add_u32 s70, s70, 0x100
	s_addc_u32 s71, s71, 0
	s_cmp_gt_u32 s76, 13
	s_cbranch_scc0 .LBB0_727
	s_and_b64 vcc, exec, s[38:39]
	s_cbranch_vccz .LBB0_730
	s_barrier

; #define PG8_STAGE(bufoff, gbase, voff) do { _Pragma("unroll") for (int _i = 0; _i < 2; ++_i) \
;         __builtin_amdgcn_global_load_lds((const unsigned*)((const char*)(gbase) + (voff)[_i]), (PG8_LAS unsigned*)(lds + (bufoff) + ldsw + _i * 8192), 16, 0, 0); } while (0)
; #define PG8_LDA(dst, b, h) do { _Pragma("unroll") for (int m = 0; m < 4; ++m) _Pragma("unroll") for (int k = 0; k < 2; ++k) dst[m][k] = *(const PG8_LAS bf16x8*)(lds + PG8_SA(b, h) + aoff + m * 2048 + k * 1024); } while (0)
; #define PG8_LDB(dst, b, h) do { _Pragma("unroll") for (int n = 0; n < 2; ++n) _Pragma("unroll") for (int k = 0; k < 2; ++k) dst[n][k] = *(const PG8_LAS bf16x8*)(lds + PG8_SB(b, h) + boff + n * 2048 + k * 1024); } while (0)
; #define PG8_MMA(ai, bj, At, Bt) do { __builtin_amdgcn_s_setprio(1); _Pragma("unroll") for (int m = 0; m < 4; ++m) _Pragma("unroll") for (int n = 0; n < 2; ++n) _Pragma("unroll") for (int k = 0; k < 2; ++k) \
;         acc[ai][bj][m][n] = __builtin_amdgcn_mfma_f32_16x16x32_bf16(Bt[n][k], At[m][k], acc[ai][bj][m][n], 0, 0, 0); __builtin_amdgcn_s_setprio(0); } while (0)
; #define PG8_WAIT_V(n) asm volatile("s_waitcnt vmcnt(" #n ")" ::: "memory")
; #define PG8_BAR __builtin_amdgcn_s_barrier()
; template <class Epi, class Sched, bool ALIGN_EPI = false, bool SP2 = false>
; __device__ __forceinline__ void gemm_phase(PG8_LAS unsigned char* lds, const Gemm g, const Sched& S, const Epi& E) {
;     ...
;         for (int t = 0; t < nt; t += 2) {
;             const bool last = (t == nt - 2);
;             const char* a1 = cA + (size_t)(t + 1) * kstep;
;             const char* a2 = last ? nA : cA + (size_t)(t + 2) * kstep; const char* b2 = last ? nB : cB + (size_t)(t + 2) * kstep;
;             const char* a3 = a2 + kstep; const char* b3 = b2 + kstep;
;             if (last && has_next) S.a_ready(nxt);
;             if constexpr (SP2) {
;             PG8_LDB(B0, 0, 0); PG8_LDB(B1, 0, 1); PG8_SCHED; PG8_LDA(At, 0, 0); PG8_STAGE(PG8_SA(1, 1), a1 + hstepA, voffA);
;             PG8_WAIT_V(8); PG8_WAIT_L(0); PG8_BAR; PG8_MMA(0, 0, At, B0); PG8_MMA(0, 1, At, B1); PG8_BAR; PG8_SCHED;
;             PG8_LDA(At, 0, 1); PG8_STAGE(PG8_SB(0, 0), b2, voffB); PG8_STAGE(PG8_SB(0, 1), b2 + hstepB, voffB); PG8_STAGE(PG8_SA(0, 0), a2, voffA);
;             PG8_WAIT_V(8); PG8_WAIT_L(0); PG8_BAR; PG8_MMA(1, 0, At, B0); PG8_MMA(1, 1, At, B1); PG8_BAR; PG8_SCHED;
.LBB0_815:
	s_add_u32 s4, s50, 0xfffc0080
	s_addc_u32 s5, s51, -1
	s_add_i32 s77, 0, 0x10000
	s_cmp_eq_u32 s76, 12
	s_cselect_b32 s35, s43, s5
	s_cselect_b32 s34, s83, s4
	s_cselect_b32 s25, s39, s91
	s_cselect_b32 s24, s89, s90
	s_add_i32 s4, 0, 0x14000
	v_add_u32_e32 v142, s77, v200
	v_add_u32_e32 v158, s4, v200
	ds_read_b128 v[130:133], v142
	ds_read_b128 v[134:137], v142 offset:1024
	ds_read_b128 v[138:141], v142 offset:2048
	ds_read_b128 v[142:145], v142 offset:3072
	ds_read_b128 v[146:149], v158
	ds_read_b128 v[150:153], v158 offset:1024
	ds_read_b128 v[154:157], v158 offset:2048
	ds_read_b128 v[158:161], v158 offset:3072
	v_lshl_add_u64 v[178:179], s[50:51], 0, v[170:171]
	s_add_i32 m0, s60, 0xc000
	ds_read_b128 v[174:177], v202
	ds_read_b128 v[186:189], v202 offset:1024
	ds_read_b128 v[190:193], v202 offset:2048
	ds_read_b128 v[194:197], v202 offset:3072
	ds_read_b128 v[204:207], v202 offset:4096
	ds_read_b128 v[208:211], v202 offset:5120
	ds_read_b128 v[212:215], v202 offset:6144
	ds_read_b128 v[216:219], v202 offset:7168
	global_load_lds_dwordx4 v[178:179], off
	v_lshl_add_u64 v[178:179], s[50:51], 0, v[172:173]
	s_add_i32 m0, s60, 0xe000
	s_nop 0
	global_load_lds_dwordx4 v[178:179], off
	s_waitcnt vmcnt(8)
	s_waitcnt lgkmcnt(0)
	s_setprio 1
	s_waitcnt lgkmcnt(0)
	s_barrier
	v_mfma_f32_16x16x32_bf16 v[126:129], v[130:133], v[174:177], v[126:129]
	v_mfma_f32_16x16x32_bf16 v[122:125], v[138:141], v[174:177], v[122:125]
	v_mfma_f32_16x16x32_bf16 v[118:121], v[130:133], v[190:193], v[118:121]
	v_mfma_f32_16x16x32_bf16 v[114:117], v[138:141], v[190:193], v[114:117]
	v_mfma_f32_16x16x32_bf16 v[94:97], v[130:133], v[204:207], v[94:97]
	v_mfma_f32_16x16x32_bf16 v[90:93], v[138:141], v[204:207], v[90:93]
	v_mfma_f32_16x16x32_bf16 v[78:81], v[130:133], v[212:215], v[78:81]
	v_mfma_f32_16x16x32_bf16 v[74:77], v[138:141], v[212:215], v[74:77]
	v_mfma_f32_16x16x32_bf16 v[126:129], v[134:137], v[186:189], v[126:129]
	v_mfma_f32_16x16x32_bf16 v[122:125], v[142:145], v[186:189], v[122:125]
	v_mfma_f32_16x16x32_bf16 v[118:121], v[134:137], v[194:197], v[118:121]
	v_mfma_f32_16x16x32_bf16 v[114:117], v[142:145], v[194:197], v[114:117]
	v_mfma_f32_16x16x32_bf16 v[94:97], v[134:137], v[208:211], v[94:97]
	v_mfma_f32_16x16x32_bf16 v[90:93], v[142:145], v[208:211], v[90:93]
	v_mfma_f32_16x16x32_bf16 v[78:81], v[134:137], v[216:219], v[78:81]
	v_mfma_f32_16x16x32_bf16 v[74:77], v[142:145], v[216:219], v[74:77]
	v_mfma_f32_16x16x32_bf16 v[110:113], v[146:149], v[174:177], v[110:113]
	v_mfma_f32_16x16x32_bf16 v[106:109], v[154:157], v[174:177], v[106:109]
	v_mfma_f32_16x16x32_bf16 v[102:105], v[146:149], v[190:193], v[102:105]
	v_mfma_f32_16x16x32_bf16 v[98:101], v[154:157], v[190:193], v[98:101]
	v_mfma_f32_16x16x32_bf16 v[86:89], v[146:149], v[204:207], v[86:89]
	v_mfma_f32_16x16x32_bf16 v[82:85], v[154:157], v[204:207], v[82:85]
	v_mfma_f32_16x16x32_bf16 v[70:73], v[146:149], v[212:215], v[70:73]
	v_mfma_f32_16x16x32_bf16 v[66:69], v[154:157], v[212:215], v[66:69]
	v_mfma_f32_16x16x32_bf16 v[110:113], v[150:153], v[186:189], v[110:113]
	v_mfma_f32_16x16x32_bf16 v[106:109], v[158:161], v[186:189], v[106:109]
	v_mfma_f32_16x16x32_bf16 v[102:105], v[150:153], v[194:197], v[102:105]
	v_mfma_f32_16x16x32_bf16 v[98:101], v[158:161], v[194:197], v[98:101]
	v_mfma_f32_16x16x32_bf16 v[86:89], v[150:153], v[208:211], v[86:89]
	v_mfma_f32_16x16x32_bf16 v[82:85], v[158:161], v[208:211], v[82:85]
	v_mfma_f32_16x16x32_bf16 v[70:73], v[150:153], v[216:219], v[70:73]
	v_mfma_f32_16x16x32_bf16 v[66:69], v[158:161], v[216:219], v[66:69]
	s_barrier
	s_setprio 0
	s_add_i32 s5, s77, s53
	v_lshl_add_u64 v[178:179], s[24:25], 0, v[166:167]
	s_mov_b32 m0, s5
	ds_read_b128 v[174:177], v202 offset:16384
	ds_read_b128 v[186:189], v202 offset:17408
	ds_read_b128 v[190:193], v202 offset:18432
	ds_read_b128 v[194:197], v202 offset:19456
	ds_read_b128 v[204:207], v202 offset:20480
	ds_read_b128 v[208:211], v202 offset:21504
	ds_read_b128 v[212:215], v202 offset:22528
	ds_read_b128 v[216:219], v202 offset:23552
	global_load_lds_dwordx4 v[178:179], off
	s_add_i32 m0, s5, 0x2000
	s_add_u32 s78, s24, 0x40000
	v_lshl_add_u64 v[198:199], s[24:25], 0, v[162:163]
	s_addc_u32 s79, s25, 0
	s_add_i32 s4, s4, s53
	global_load_lds_dwordx4 v[198:199], off
	v_lshl_add_u64 v[220:221], s[78:79], 0, v[166:167]
	s_mov_b32 m0, s4
	v_lshl_add_u64 v[234:235], s[34:35], 0, v[164:165]
	global_load_lds_dwordx4 v[220:221], off
	v_lshl_add_u64 v[220:221], s[78:79], 0, v[162:163]
	s_add_i32 m0, s4, 0x2000
	s_nop 0
	global_load_lds_dwordx4 v[220:221], off
	v_lshl_add_u64 v[220:221], s[34:35], 0, v[168:169]
	s_mov_b32 m0, s60
	s_nop 0
	global_load_lds_dwordx4 v[220:221], off
	s_mov_b32 m0, s61
	s_nop 0
	global_load_lds_dwordx4 v[234:235], off
	s_waitcnt vmcnt(8)
	s_waitcnt lgkmcnt(0)
	s_setprio 1
	s_waitcnt lgkmcnt(0)
	s_barrier
; #define PG8_STAGE(bufoff, gbase, voff) do { _Pragma("unroll") for (int _i = 0; _i < 2; ++_i) \
;         __builtin_amdgcn_global_load_lds((const unsigned*)((const char*)(gbase) + (voff)[_i]), (PG8_LAS unsigned*)(lds + (bufoff) + ldsw + _i * 8192), 16, 0, 0); } while (0)
; #define PG8_LDA(dst, b, h) do { _Pragma("unroll") for (int m = 0; m < 4; ++m) _Pragma("unroll") for (int k = 0; k < 2; ++k) dst[m][k] = *(const PG8_LAS bf16x8*)(lds + PG8_SA(b, h) + aoff + m * 2048 + k * 1024); } while (0)
; #define PG8_LDB(dst, b, h) do { _Pragma("unroll") for (int n = 0; n < 2; ++n) _Pragma("unroll") for (int k = 0; k < 2; ++k) dst[n][k] = *(const PG8_LAS bf16x8*)(lds + PG8_SB(b, h) + boff + n * 2048 + k * 1024); } while (0)
; #define PG8_MMA(ai, bj, At, Bt) do { __builtin_amdgcn_s_setprio(1); _Pragma("unroll") for (int m = 0; m < 4; ++m) _Pragma("unroll") for (int n = 0; n < 2; ++n) _Pragma("unroll") for (int k = 0; k < 2; ++k) \
;         acc[ai][bj][m][n] = __builtin_amdgcn_mfma_f32_16x16x32_bf16(Bt[n][k], At[m][k], acc[ai][bj][m][n], 0, 0, 0); __builtin_amdgcn_s_setprio(0); } while (0)
; #define PG8_WAIT_V(n) asm volatile("s_waitcnt vmcnt(" #n ")" ::: "memory")
; #define PG8_WAIT_L(n) asm volatile("s_waitcnt lgkmcnt(" #n ")" ::: "memory")
; #define PG8_BAR __builtin_amdgcn_s_barrier()
; #define PG8_SCHED __builtin_amdgcn_sched_barrier(0)
; template <class Epi, class Sched, bool ALIGN_EPI = false, bool SP2 = false>
; __device__ __forceinline__ void gemm_phase(PG8_LAS unsigned char* lds, const Gemm g, const Sched& S, const Epi& E) {
;     ...
;             PG8_WAIT_V(8); PG8_WAIT_L(0); PG8_BAR; PG8_MMA(1, 0, At, B0); PG8_MMA(1, 1, At, B1); PG8_BAR; PG8_SCHED;
;             PG8_LDB(B0, 1, 0); PG8_LDB(B1, 1, 1); PG8_SCHED; PG8_LDA(At, 1, 0); PG8_STAGE(PG8_SA(0, 1), a2 + hstepA, voffA);
;             PG8_WAIT_V(8); PG8_WAIT_L(0); PG8_BAR; PG8_MMA(0, 0, At, B0); PG8_MMA(0, 1, At, B1); PG8_BAR; PG8_SCHED;
	v_mfma_f32_16x16x32_bf16 v[62:65], v[130:133], v[174:177], v[62:65]
	v_mfma_f32_16x16x32_bf16 v[58:61], v[138:141], v[174:177], v[58:61]
	v_mfma_f32_16x16x32_bf16 v[46:49], v[130:133], v[190:193], v[46:49]
	v_mfma_f32_16x16x32_bf16 v[42:45], v[138:141], v[190:193], v[42:45]
	v_mfma_f32_16x16x32_bf16 v[30:33], v[130:133], v[204:207], v[30:33]
	v_mfma_f32_16x16x32_bf16 v[26:29], v[138:141], v[204:207], v[26:29]
	v_mfma_f32_16x16x32_bf16 v[14:17], v[130:133], v[212:215], v[14:17]
	v_mfma_f32_16x16x32_bf16 v[10:13], v[138:141], v[212:215], v[10:13]
	v_mfma_f32_16x16x32_bf16 v[62:65], v[134:137], v[186:189], v[62:65]
	v_mfma_f32_16x16x32_bf16 v[58:61], v[142:145], v[186:189], v[58:61]
	v_mfma_f32_16x16x32_bf16 v[46:49], v[134:137], v[194:197], v[46:49]
	v_mfma_f32_16x16x32_bf16 v[42:45], v[142:145], v[194:197], v[42:45]
	v_mfma_f32_16x16x32_bf16 v[30:33], v[134:137], v[208:211], v[30:33]
	v_mfma_f32_16x16x32_bf16 v[26:29], v[142:145], v[208:211], v[26:29]
	v_mfma_f32_16x16x32_bf16 v[14:17], v[134:137], v[216:219], v[14:17]
	v_mfma_f32_16x16x32_bf16 v[10:13], v[142:145], v[216:219], v[10:13]
	v_mfma_f32_16x16x32_bf16 v[54:57], v[146:149], v[174:177], v[54:57]
	v_mfma_f32_16x16x32_bf16 v[50:53], v[154:157], v[174:177], v[50:53]
	v_mfma_f32_16x16x32_bf16 v[38:41], v[146:149], v[190:193], v[38:41]
	v_mfma_f32_16x16x32_bf16 v[34:37], v[154:157], v[190:193], v[34:37]
	v_mfma_f32_16x16x32_bf16 v[22:25], v[146:149], v[204:207], v[22:25]
	v_mfma_f32_16x16x32_bf16 v[18:21], v[154:157], v[204:207], v[18:21]
	v_mfma_f32_16x16x32_bf16 v[6:9], v[146:149], v[212:215], v[6:9]
	v_mfma_f32_16x16x32_bf16 v[2:5], v[154:157], v[212:215], v[2:5]
	v_mfma_f32_16x16x32_bf16 v[54:57], v[150:153], v[186:189], v[54:57]
	v_mfma_f32_16x16x32_bf16 v[50:53], v[158:161], v[186:189], v[50:53]
	v_mfma_f32_16x16x32_bf16 v[38:41], v[150:153], v[194:197], v[38:41]
	v_mfma_f32_16x16x32_bf16 v[34:37], v[158:161], v[194:197], v[34:37]
	v_mfma_f32_16x16x32_bf16 v[22:25], v[150:153], v[208:211], v[22:25]
	v_mfma_f32_16x16x32_bf16 v[18:21], v[158:161], v[208:211], v[18:21]
	v_mfma_f32_16x16x32_bf16 v[6:9], v[150:153], v[216:219], v[6:9]
	v_mfma_f32_16x16x32_bf16 v[2:5], v[158:161], v[216:219], v[2:5]
	s_barrier
	s_setprio 0
	s_add_i32 s4, 0, 0x18000
	s_add_i32 s5, 0, 0x1c000
	v_add_u32_e32 v142, s4, v200
	v_add_u32_e32 v158, s5, v200
	ds_read_b128 v[130:133], v142
	ds_read_b128 v[134:137], v142 offset:1024
	ds_read_b128 v[138:141], v142 offset:2048
	ds_read_b128 v[142:145], v142 offset:3072
	ds_read_b128 v[146:149], v158
	ds_read_b128 v[150:153], v158 offset:1024
	ds_read_b128 v[154:157], v158 offset:2048
	ds_read_b128 v[158:161], v158 offset:3072
	s_add_u32 s34, s34, 0x40000
	s_addc_u32 s35, s35, 0
	s_mov_b32 m0, s70
	v_lshl_add_u64 v[236:237], s[34:35], 0, v[168:169]
	ds_read_b128 v[174:177], v202 offset:32768
	ds_read_b128 v[186:189], v202 offset:33792
	ds_read_b128 v[190:193], v202 offset:34816
	ds_read_b128 v[194:197], v202 offset:35840
	ds_read_b128 v[204:207], v202 offset:36864
	ds_read_b128 v[208:211], v202 offset:37888
	ds_read_b128 v[212:215], v202 offset:38912
	ds_read_b128 v[216:219], v202 offset:39936
	global_load_lds_dwordx4 v[236:237], off
	v_lshl_add_u64 v[236:237], s[34:35], 0, v[164:165]
	s_mov_b32 m0, s71
	s_nop 0
	global_load_lds_dwordx4 v[236:237], off
	s_waitcnt vmcnt(8)
	s_waitcnt lgkmcnt(0)
	s_setprio 1
	s_waitcnt lgkmcnt(0)
	s_barrier
	v_mfma_f32_16x16x32_bf16 v[126:129], v[130:133], v[174:177], v[126:129]
	v_mfma_f32_16x16x32_bf16 v[122:125], v[138:141], v[174:177], v[122:125]
	v_mfma_f32_16x16x32_bf16 v[118:121], v[130:133], v[190:193], v[118:121]
	v_mfma_f32_16x16x32_bf16 v[114:117], v[138:141], v[190:193], v[114:117]
	v_mfma_f32_16x16x32_bf16 v[94:97], v[130:133], v[204:207], v[94:97]
	v_mfma_f32_16x16x32_bf16 v[90:93], v[138:141], v[204:207], v[90:93]
	v_mfma_f32_16x16x32_bf16 v[78:81], v[130:133], v[212:215], v[78:81]
	v_mfma_f32_16x16x32_bf16 v[74:77], v[138:141], v[212:215], v[74:77]
	v_mfma_f32_16x16x32_bf16 v[126:129], v[134:137], v[186:189], v[126:129]
	v_mfma_f32_16x16x32_bf16 v[122:125], v[142:145], v[186:189], v[122:125]
	v_mfma_f32_16x16x32_bf16 v[118:121], v[134:137], v[194:197], v[118:121]
	v_mfma_f32_16x16x32_bf16 v[114:117], v[142:145], v[194:197], v[114:117]
	v_mfma_f32_16x16x32_bf16 v[94:97], v[134:137], v[208:211], v[94:97]
	v_mfma_f32_16x16x32_bf16 v[90:93], v[142:145], v[208:211], v[90:93]
	v_mfma_f32_16x16x32_bf16 v[78:81], v[134:137], v[216:219], v[78:81]
	v_mfma_f32_16x16x32_bf16 v[74:77], v[142:145], v[216:219], v[74:77]
	v_mfma_f32_16x16x32_bf16 v[110:113], v[146:149], v[174:177], v[110:113]
	v_mfma_f32_16x16x32_bf16 v[106:109], v[154:157], v[174:177], v[106:109]
	v_mfma_f32_16x16x32_bf16 v[102:105], v[146:149], v[190:193], v[102:105]
	v_mfma_f32_16x16x32_bf16 v[98:101], v[154:157], v[190:193], v[98:101]
	v_mfma_f32_16x16x32_bf16 v[86:89], v[146:149], v[204:207], v[86:89]
	v_mfma_f32_16x16x32_bf16 v[82:85], v[154:157], v[204:207], v[82:85]
	v_mfma_f32_16x16x32_bf16 v[70:73], v[146:149], v[212:215], v[70:73]
	v_mfma_f32_16x16x32_bf16 v[66:69], v[154:157], v[212:215], v[66:69]
	v_mfma_f32_16x16x32_bf16 v[110:113], v[150:153], v[186:189], v[110:113]
	v_mfma_f32_16x16x32_bf16 v[106:109], v[158:161], v[186:189], v[106:109]
	v_mfma_f32_16x16x32_bf16 v[102:105], v[150:153], v[194:197], v[102:105]
	v_mfma_f32_16x16x32_bf16 v[98:101], v[158:161], v[194:197], v[98:101]
	v_mfma_f32_16x16x32_bf16 v[86:89], v[150:153], v[208:211], v[86:89]
	v_mfma_f32_16x16x32_bf16 v[82:85], v[158:161], v[208:211], v[82:85]
	v_mfma_f32_16x16x32_bf16 v[70:73], v[150:153], v[216:219], v[70:73]
	v_mfma_f32_16x16x32_bf16 v[66:69], v[158:161], v[216:219], v[66:69]
	s_barrier
; #define PG8_STAGE(bufoff, gbase, voff) do { _Pragma("unroll") for (int _i = 0; _i < 2; ++_i) \
;         __builtin_amdgcn_global_load_lds((const unsigned*)((const char*)(gbase) + (voff)[_i]), (PG8_LAS unsigned*)(lds + (bufoff) + ldsw + _i * 8192), 16, 0, 0); } while (0)
; #define PG8_LDA(dst, b, h) do { _Pragma("unroll") for (int m = 0; m < 4; ++m) _Pragma("unroll") for (int k = 0; k < 2; ++k) dst[m][k] = *(const PG8_LAS bf16x8*)(lds + PG8_SA(b, h) + aoff + m * 2048 + k * 1024); } while (0)
; #define PG8_MMA(ai, bj, At, Bt) do { __builtin_amdgcn_s_setprio(1); _Pragma("unroll") for (int m = 0; m < 4; ++m) _Pragma("unroll") for (int n = 0; n < 2; ++n) _Pragma("unroll") for (int k = 0; k < 2; ++k) \
;         acc[ai][bj][m][n] = __builtin_amdgcn_mfma_f32_16x16x32_bf16(Bt[n][k], At[m][k], acc[ai][bj][m][n], 0, 0, 0); __builtin_amdgcn_s_setprio(0); } while (0)
; #define PG8_WAIT_V(n) asm volatile("s_waitcnt vmcnt(" #n ")" ::: "memory")
; #define PG8_WAIT_L(n) asm volatile("s_waitcnt lgkmcnt(" #n ")" ::: "memory")
; #define PG8_BAR __builtin_amdgcn_s_barrier()
; #define PG8_SCHED __builtin_amdgcn_sched_barrier(0)
; template <class Epi, class Sched, bool ALIGN_EPI = false, bool SP2 = false>
; __device__ __forceinline__ void gemm_phase(PG8_LAS unsigned char* lds, const Gemm g, const Sched& S, const Epi& E) {
;     ...
;             PG8_WAIT_V(8); PG8_WAIT_L(0); PG8_BAR; PG8_MMA(0, 0, At, B0); PG8_MMA(0, 1, At, B1); PG8_BAR; PG8_SCHED;
;             PG8_LDA(At, 1, 1); PG8_STAGE(PG8_SB(1, 0), b3, voffB); PG8_STAGE(PG8_SB(1, 1), b3 + hstepB, voffB); PG8_STAGE(PG8_SA(1, 0), a3, voffA);
;             PG8_WAIT_V(8); PG8_WAIT_L(0); PG8_BAR; PG8_MMA(1, 0, At, B0); PG8_MMA(1, 1, At, B1); PG8_BAR; PG8_SCHED;
;     ...
;         if constexpr (ALIGN_EPI) { if (wr == 0) PG8_BAR; }
	s_setprio 0
	s_add_i32 s4, s4, s53
	v_lshl_add_u64 v[178:179], v[178:179], 0, s[62:63]
	s_mov_b32 m0, s4
	ds_read_b128 v[174:177], v202 offset:49152
	ds_read_b128 v[186:189], v202 offset:50176
	ds_read_b128 v[190:193], v202 offset:51200
	ds_read_b128 v[194:197], v202 offset:52224
	ds_read_b128 v[204:207], v202 offset:53248
	ds_read_b128 v[208:211], v202 offset:54272
	ds_read_b128 v[212:215], v202 offset:55296
	ds_read_b128 v[216:219], v202 offset:56320
	global_load_lds_dwordx4 v[178:179], off
	s_add_i32 m0, s4, 0x2000
	s_add_u32 s24, s24, 0x40080
	v_lshl_add_u64 v[178:179], v[198:199], 0, s[62:63]
	s_addc_u32 s25, s25, 0
	s_add_i32 s4, s5, s53
	global_load_lds_dwordx4 v[178:179], off
	v_lshl_add_u64 v[178:179], s[24:25], 0, v[166:167]
	s_mov_b32 m0, s4
	s_nop 0
	global_load_lds_dwordx4 v[178:179], off
	v_lshl_add_u64 v[178:179], s[24:25], 0, v[162:163]
	s_add_i32 m0, s4, 0x2000
	s_nop 0
	global_load_lds_dwordx4 v[178:179], off
	v_lshl_add_u64 v[178:179], v[220:221], 0, s[62:63]
	s_mov_b32 m0, s74
	s_nop 0
	global_load_lds_dwordx4 v[178:179], off
	v_lshl_add_u64 v[178:179], v[234:235], 0, s[62:63]
	s_mov_b32 m0, s75
	s_nop 0
	global_load_lds_dwordx4 v[178:179], off
	s_waitcnt vmcnt(8)
	s_waitcnt lgkmcnt(0)
	s_setprio 1
	s_waitcnt lgkmcnt(0)
	s_barrier
	v_mfma_f32_16x16x32_bf16 v[62:65], v[130:133], v[174:177], v[62:65]
	v_mfma_f32_16x16x32_bf16 v[58:61], v[138:141], v[174:177], v[58:61]
	v_mfma_f32_16x16x32_bf16 v[46:49], v[130:133], v[190:193], v[46:49]
	v_mfma_f32_16x16x32_bf16 v[42:45], v[138:141], v[190:193], v[42:45]
	v_mfma_f32_16x16x32_bf16 v[30:33], v[130:133], v[204:207], v[30:33]
	v_mfma_f32_16x16x32_bf16 v[26:29], v[138:141], v[204:207], v[26:29]
	v_mfma_f32_16x16x32_bf16 v[14:17], v[130:133], v[212:215], v[14:17]
	v_mfma_f32_16x16x32_bf16 v[10:13], v[138:141], v[212:215], v[10:13]
	v_mfma_f32_16x16x32_bf16 v[62:65], v[134:137], v[186:189], v[62:65]
	v_mfma_f32_16x16x32_bf16 v[58:61], v[142:145], v[186:189], v[58:61]
	v_mfma_f32_16x16x32_bf16 v[46:49], v[134:137], v[194:197], v[46:49]
	v_mfma_f32_16x16x32_bf16 v[42:45], v[142:145], v[194:197], v[42:45]
	v_mfma_f32_16x16x32_bf16 v[30:33], v[134:137], v[208:211], v[30:33]
	v_mfma_f32_16x16x32_bf16 v[26:29], v[142:145], v[208:211], v[26:29]
	v_mfma_f32_16x16x32_bf16 v[14:17], v[134:137], v[216:219], v[14:17]
	v_mfma_f32_16x16x32_bf16 v[10:13], v[142:145], v[216:219], v[10:13]
	v_mfma_f32_16x16x32_bf16 v[54:57], v[146:149], v[174:177], v[54:57]
	v_mfma_f32_16x16x32_bf16 v[50:53], v[154:157], v[174:177], v[50:53]
	v_mfma_f32_16x16x32_bf16 v[38:41], v[146:149], v[190:193], v[38:41]
	v_mfma_f32_16x16x32_bf16 v[34:37], v[154:157], v[190:193], v[34:37]
	v_mfma_f32_16x16x32_bf16 v[22:25], v[146:149], v[204:207], v[22:25]
	v_mfma_f32_16x16x32_bf16 v[18:21], v[154:157], v[204:207], v[18:21]
	v_mfma_f32_16x16x32_bf16 v[6:9], v[146:149], v[212:215], v[6:9]
	v_mfma_f32_16x16x32_bf16 v[2:5], v[154:157], v[212:215], v[2:5]
	v_mfma_f32_16x16x32_bf16 v[54:57], v[150:153], v[186:189], v[54:57]
	v_mfma_f32_16x16x32_bf16 v[50:53], v[158:161], v[186:189], v[50:53]
	v_mfma_f32_16x16x32_bf16 v[38:41], v[150:153], v[194:197], v[38:41]
	v_mfma_f32_16x16x32_bf16 v[34:37], v[158:161], v[194:197], v[34:37]
	v_mfma_f32_16x16x32_bf16 v[22:25], v[150:153], v[208:211], v[22:25]
	v_mfma_f32_16x16x32_bf16 v[18:21], v[158:161], v[208:211], v[18:21]
	v_mfma_f32_16x16x32_bf16 v[6:9], v[150:153], v[216:219], v[6:9]
	v_mfma_f32_16x16x32_bf16 v[2:5], v[158:161], v[216:219], v[2:5]
	s_barrier
	s_setprio 0
	s_add_i32 s76, s76, 2
	s_add_u32 s50, s50, 0x100
	s_addc_u32 s51, s51, 0
	s_add_u32 s90, s90, 0x100
	s_addc_u32 s91, s91, 0
	s_cmp_gt_u32 s76, 13
	s_cbranch_scc0 .LBB0_815
	s_and_b64 vcc, exec, s[30:31]
	s_cbranch_vccz .LBB0_818
	s_barrier

; #define PG8_STAGE(bufoff, gbase, voff) do { _Pragma("unroll") for (int _i = 0; _i < 2; ++_i) \
;         __builtin_amdgcn_global_load_lds((const unsigned*)((const char*)(gbase) + (voff)[_i]), (PG8_LAS unsigned*)(lds + (bufoff) + ldsw + _i * 8192), 16, 0, 0); } while (0)
; #define PG8_LDA(dst, b, h) do { _Pragma("unroll") for (int m = 0; m < 4; ++m) _Pragma("unroll") for (int k = 0; k < 2; ++k) dst[m][k] = *(const PG8_LAS bf16x8*)(lds + PG8_SA(b, h) + aoff + m * 2048 + k * 1024); } while (0)
; #define PG8_LDB(dst, b, h) do { _Pragma("unroll") for (int n = 0; n < 2; ++n) _Pragma("unroll") for (int k = 0; k < 2; ++k) dst[n][k] = *(const PG8_LAS bf16x8*)(lds + PG8_SB(b, h) + boff + n * 2048 + k * 1024); } while (0)
; #define PG8_MMA(ai, bj, At, Bt) do { __builtin_amdgcn_s_setprio(1); _Pragma("unroll") for (int m = 0; m < 4; ++m) _Pragma("unroll") for (int n = 0; n < 2; ++n) _Pragma("unroll") for (int k = 0; k < 2; ++k) \
;         acc[ai][bj][m][n] = __builtin_amdgcn_mfma_f32_16x16x32_bf16(Bt[n][k], At[m][k], acc[ai][bj][m][n], 0, 0, 0); __builtin_amdgcn_s_setprio(0); } while (0)
; #define PG8_WAIT_V(n) asm volatile("s_waitcnt vmcnt(" #n ")" ::: "memory")
; #define PG8_BAR __builtin_amdgcn_s_barrier()
; template <class Epi, class Sched, bool ALIGN_EPI = false, bool SP2 = false>
; __device__ __forceinline__ void gemm_phase(PG8_LAS unsigned char* lds, const Gemm g, const Sched& S, const Epi& E) {
;     ...
;         for (int t = 0; t < nt; t += 2) {
;             const bool last = (t == nt - 2);
;             const char* a1 = cA + (size_t)(t + 1) * kstep;
;             const char* a2 = last ? nA : cA + (size_t)(t + 2) * kstep; const char* b2 = last ? nB : cB + (size_t)(t + 2) * kstep;
;             const char* a3 = a2 + kstep; const char* b3 = b2 + kstep;
;             if (last && has_next) S.a_ready(nxt);
;             if constexpr (SP2) {
;             PG8_LDB(B0, 0, 0); PG8_LDB(B1, 0, 1); PG8_SCHED; PG8_LDA(At, 0, 0); PG8_STAGE(PG8_SA(1, 1), a1 + hstepA, voffA);
;             PG8_WAIT_V(8); PG8_WAIT_L(0); PG8_BAR; PG8_MMA(0, 0, At, B0); PG8_MMA(0, 1, At, B1); PG8_BAR; PG8_SCHED;
;             PG8_LDA(At, 0, 1); PG8_STAGE(PG8_SB(0, 0), b2, voffB); PG8_STAGE(PG8_SB(0, 1), b2 + hstepB, voffB); PG8_STAGE(PG8_SA(0, 0), a2, voffA);
;             PG8_WAIT_V(8); PG8_WAIT_L(0); PG8_BAR; PG8_MMA(1, 0, At, B0); PG8_MMA(1, 1, At, B1); PG8_BAR; PG8_SCHED;
.LBB0_971:
	s_add_u32 s42, s50, 0x100
	s_addc_u32 s43, s51, 0
	s_add_i32 s4, 0, 0x10000
	s_cmp_eq_u32 s76, 40
	s_cselect_b32 s35, s47, s43
	s_cselect_b32 s34, s46, s42
	s_cselect_b32 s25, s49, s53
	s_cselect_b32 s24, s48, s52
	s_add_i32 s5, 0, 0x14000
	v_add_u32_e32 v142, s4, v171
	v_add_u32_e32 v158, s5, v171
	ds_read_b128 v[130:133], v142
	ds_read_b128 v[134:137], v142 offset:1024
	ds_read_b128 v[138:141], v142 offset:2048
	ds_read_b128 v[142:145], v142 offset:3072
	ds_read_b128 v[146:149], v158
	ds_read_b128 v[150:153], v158 offset:1024
	ds_read_b128 v[154:157], v158 offset:2048
	ds_read_b128 v[158:161], v158 offset:3072
	v_lshl_add_u64 v[220:221], s[50:51], 0, v[178:179]
	s_add_i32 m0, s70, 0xc000
	ds_read_b128 v[188:191], v233
	ds_read_b128 v[192:195], v233 offset:1024
	ds_read_b128 v[196:199], v233 offset:2048
	ds_read_b128 v[200:203], v233 offset:3072
	ds_read_b128 v[204:207], v233 offset:4096
	ds_read_b128 v[208:211], v233 offset:5120
	ds_read_b128 v[212:215], v233 offset:6144
	ds_read_b128 v[216:219], v233 offset:7168
	global_load_lds_dwordx4 v[220:221], off
	v_lshl_add_u64 v[220:221], s[50:51], 0, v[186:187]
	s_add_i32 m0, s70, 0xe000
	s_nop 0
	global_load_lds_dwordx4 v[220:221], off
	s_waitcnt vmcnt(8)
	s_waitcnt lgkmcnt(0)
	s_setprio 1
	s_waitcnt lgkmcnt(0)
	s_barrier
	v_mfma_f32_16x16x32_bf16 v[126:129], v[130:133], v[188:191], v[126:129]
	v_mfma_f32_16x16x32_bf16 v[122:125], v[138:141], v[188:191], v[122:125]
	v_mfma_f32_16x16x32_bf16 v[110:113], v[130:133], v[196:199], v[110:113]
	v_mfma_f32_16x16x32_bf16 v[106:109], v[138:141], v[196:199], v[106:109]
	v_mfma_f32_16x16x32_bf16 v[94:97], v[130:133], v[204:207], v[94:97]
	v_mfma_f32_16x16x32_bf16 v[90:93], v[138:141], v[204:207], v[90:93]
	v_mfma_f32_16x16x32_bf16 v[78:81], v[130:133], v[212:215], v[78:81]
	v_mfma_f32_16x16x32_bf16 v[74:77], v[138:141], v[212:215], v[74:77]
	v_mfma_f32_16x16x32_bf16 v[126:129], v[134:137], v[192:195], v[126:129]
	v_mfma_f32_16x16x32_bf16 v[122:125], v[142:145], v[192:195], v[122:125]
	v_mfma_f32_16x16x32_bf16 v[110:113], v[134:137], v[200:203], v[110:113]
	v_mfma_f32_16x16x32_bf16 v[106:109], v[142:145], v[200:203], v[106:109]
	v_mfma_f32_16x16x32_bf16 v[94:97], v[134:137], v[208:211], v[94:97]
	v_mfma_f32_16x16x32_bf16 v[90:93], v[142:145], v[208:211], v[90:93]
	v_mfma_f32_16x16x32_bf16 v[78:81], v[134:137], v[216:219], v[78:81]
	v_mfma_f32_16x16x32_bf16 v[74:77], v[142:145], v[216:219], v[74:77]
	v_mfma_f32_16x16x32_bf16 v[118:121], v[146:149], v[188:191], v[118:121]
	v_mfma_f32_16x16x32_bf16 v[114:117], v[154:157], v[188:191], v[114:117]
	v_mfma_f32_16x16x32_bf16 v[102:105], v[146:149], v[196:199], v[102:105]
	v_mfma_f32_16x16x32_bf16 v[98:101], v[154:157], v[196:199], v[98:101]
	v_mfma_f32_16x16x32_bf16 v[86:89], v[146:149], v[204:207], v[86:89]
	v_mfma_f32_16x16x32_bf16 v[82:85], v[154:157], v[204:207], v[82:85]
	v_mfma_f32_16x16x32_bf16 v[70:73], v[146:149], v[212:215], v[70:73]
	v_mfma_f32_16x16x32_bf16 v[66:69], v[154:157], v[212:215], v[66:69]
	v_mfma_f32_16x16x32_bf16 v[118:121], v[150:153], v[192:195], v[118:121]
	v_mfma_f32_16x16x32_bf16 v[114:117], v[158:161], v[192:195], v[114:117]
	v_mfma_f32_16x16x32_bf16 v[102:105], v[150:153], v[200:203], v[102:105]
	v_mfma_f32_16x16x32_bf16 v[98:101], v[158:161], v[200:203], v[98:101]
	v_mfma_f32_16x16x32_bf16 v[86:89], v[150:153], v[208:211], v[86:89]
	v_mfma_f32_16x16x32_bf16 v[82:85], v[158:161], v[208:211], v[82:85]
	v_mfma_f32_16x16x32_bf16 v[70:73], v[150:153], v[216:219], v[70:73]
	v_mfma_f32_16x16x32_bf16 v[66:69], v[158:161], v[216:219], v[66:69]
	s_barrier
	s_setprio 0
	s_add_i32 s4, s4, s61
	v_lshl_add_u64 v[220:221], s[24:25], 0, v[166:167]
	s_mov_b32 m0, s4
	ds_read_b128 v[188:191], v233 offset:16384
	ds_read_b128 v[192:195], v233 offset:17408
	ds_read_b128 v[196:199], v233 offset:18432
	ds_read_b128 v[200:203], v233 offset:19456
	ds_read_b128 v[204:207], v233 offset:20480
	ds_read_b128 v[208:211], v233 offset:21504
	ds_read_b128 v[212:215], v233 offset:22528
	ds_read_b128 v[216:219], v233 offset:23552
	global_load_lds_dwordx4 v[220:221], off
	s_add_i32 m0, s4, 0x2000
	s_add_u32 s50, s24, 0xb0000
	v_lshl_add_u64 v[234:235], s[24:25], 0, v[162:163]
	s_addc_u32 s51, s25, 0
	s_add_i32 s4, s5, s61
	global_load_lds_dwordx4 v[234:235], off
	v_lshl_add_u64 v[236:237], s[50:51], 0, v[166:167]
	s_mov_b32 m0, s4
	v_lshl_add_u64 v[238:239], s[34:35], 0, v[164:165]
	global_load_lds_dwordx4 v[236:237], off
	v_lshl_add_u64 v[236:237], s[50:51], 0, v[162:163]
	s_add_i32 m0, s4, 0x2000
	s_nop 0
	global_load_lds_dwordx4 v[236:237], off
	v_lshl_add_u64 v[236:237], s[34:35], 0, v[168:169]
	s_mov_b32 m0, s70
	s_nop 0
	global_load_lds_dwordx4 v[236:237], off
	s_mov_b32 m0, s71
	s_nop 0
	global_load_lds_dwordx4 v[238:239], off
	s_waitcnt vmcnt(8)
	s_waitcnt lgkmcnt(0)
	s_setprio 1
	s_waitcnt lgkmcnt(0)
	s_barrier
; #define PG8_STAGE(bufoff, gbase, voff) do { _Pragma("unroll") for (int _i = 0; _i < 2; ++_i) \
;         __builtin_amdgcn_global_load_lds((const unsigned*)((const char*)(gbase) + (voff)[_i]), (PG8_LAS unsigned*)(lds + (bufoff) + ldsw + _i * 8192), 16, 0, 0); } while (0)
; #define PG8_LDA(dst, b, h) do { _Pragma("unroll") for (int m = 0; m < 4; ++m) _Pragma("unroll") for (int k = 0; k < 2; ++k) dst[m][k] = *(const PG8_LAS bf16x8*)(lds + PG8_SA(b, h) + aoff + m * 2048 + k * 1024); } while (0)
; #define PG8_LDB(dst, b, h) do { _Pragma("unroll") for (int n = 0; n < 2; ++n) _Pragma("unroll") for (int k = 0; k < 2; ++k) dst[n][k] = *(const PG8_LAS bf16x8*)(lds + PG8_SB(b, h) + boff + n * 2048 + k * 1024); } while (0)
; #define PG8_MMA(ai, bj, At, Bt) do { __builtin_amdgcn_s_setprio(1); _Pragma("unroll") for (int m = 0; m < 4; ++m) _Pragma("unroll") for (int n = 0; n < 2; ++n) _Pragma("unroll") for (int k = 0; k < 2; ++k) \
;         acc[ai][bj][m][n] = __builtin_amdgcn_mfma_f32_16x16x32_bf16(Bt[n][k], At[m][k], acc[ai][bj][m][n], 0, 0, 0); __builtin_amdgcn_s_setprio(0); } while (0)
; #define PG8_WAIT_V(n) asm volatile("s_waitcnt vmcnt(" #n ")" ::: "memory")
; #define PG8_WAIT_L(n) asm volatile("s_waitcnt lgkmcnt(" #n ")" ::: "memory")
; #define PG8_BAR __builtin_amdgcn_s_barrier()
; #define PG8_SCHED __builtin_amdgcn_sched_barrier(0)
; template <class Epi, class Sched, bool ALIGN_EPI = false, bool SP2 = false>
; __device__ __forceinline__ void gemm_phase(PG8_LAS unsigned char* lds, const Gemm g, const Sched& S, const Epi& E) {
;     ...
;             PG8_WAIT_V(8); PG8_WAIT_L(0); PG8_BAR; PG8_MMA(1, 0, At, B0); PG8_MMA(1, 1, At, B1); PG8_BAR; PG8_SCHED;
;             PG8_LDB(B0, 1, 0); PG8_LDB(B1, 1, 1); PG8_SCHED; PG8_LDA(At, 1, 0); PG8_STAGE(PG8_SA(0, 1), a2 + hstepA, voffA);
;             PG8_WAIT_V(8); PG8_WAIT_L(0); PG8_BAR; PG8_MMA(0, 0, At, B0); PG8_MMA(0, 1, At, B1); PG8_BAR; PG8_SCHED;
	v_mfma_f32_16x16x32_bf16 v[62:65], v[130:133], v[188:191], v[62:65]
	v_mfma_f32_16x16x32_bf16 v[58:61], v[138:141], v[188:191], v[58:61]
	v_mfma_f32_16x16x32_bf16 v[46:49], v[130:133], v[196:199], v[46:49]
	v_mfma_f32_16x16x32_bf16 v[42:45], v[138:141], v[196:199], v[42:45]
	v_mfma_f32_16x16x32_bf16 v[30:33], v[130:133], v[204:207], v[30:33]
	v_mfma_f32_16x16x32_bf16 v[26:29], v[138:141], v[204:207], v[26:29]
	v_mfma_f32_16x16x32_bf16 v[14:17], v[130:133], v[212:215], v[14:17]
	v_mfma_f32_16x16x32_bf16 v[10:13], v[138:141], v[212:215], v[10:13]
	v_mfma_f32_16x16x32_bf16 v[62:65], v[134:137], v[192:195], v[62:65]
	v_mfma_f32_16x16x32_bf16 v[58:61], v[142:145], v[192:195], v[58:61]
	v_mfma_f32_16x16x32_bf16 v[46:49], v[134:137], v[200:203], v[46:49]
	v_mfma_f32_16x16x32_bf16 v[42:45], v[142:145], v[200:203], v[42:45]
	v_mfma_f32_16x16x32_bf16 v[30:33], v[134:137], v[208:211], v[30:33]
	v_mfma_f32_16x16x32_bf16 v[26:29], v[142:145], v[208:211], v[26:29]
	v_mfma_f32_16x16x32_bf16 v[14:17], v[134:137], v[216:219], v[14:17]
	v_mfma_f32_16x16x32_bf16 v[10:13], v[142:145], v[216:219], v[10:13]
	v_mfma_f32_16x16x32_bf16 v[54:57], v[146:149], v[188:191], v[54:57]
	v_mfma_f32_16x16x32_bf16 v[50:53], v[154:157], v[188:191], v[50:53]
	v_mfma_f32_16x16x32_bf16 v[38:41], v[146:149], v[196:199], v[38:41]
	v_mfma_f32_16x16x32_bf16 v[34:37], v[154:157], v[196:199], v[34:37]
	v_mfma_f32_16x16x32_bf16 v[22:25], v[146:149], v[204:207], v[22:25]
	v_mfma_f32_16x16x32_bf16 v[18:21], v[154:157], v[204:207], v[18:21]
	v_mfma_f32_16x16x32_bf16 v[6:9], v[146:149], v[212:215], v[6:9]
	v_mfma_f32_16x16x32_bf16 v[2:5], v[154:157], v[212:215], v[2:5]
	v_mfma_f32_16x16x32_bf16 v[54:57], v[150:153], v[192:195], v[54:57]
	v_mfma_f32_16x16x32_bf16 v[50:53], v[158:161], v[192:195], v[50:53]
	v_mfma_f32_16x16x32_bf16 v[38:41], v[150:153], v[200:203], v[38:41]
	v_mfma_f32_16x16x32_bf16 v[34:37], v[158:161], v[200:203], v[34:37]
	v_mfma_f32_16x16x32_bf16 v[22:25], v[150:153], v[208:211], v[22:25]
	v_mfma_f32_16x16x32_bf16 v[18:21], v[158:161], v[208:211], v[18:21]
	v_mfma_f32_16x16x32_bf16 v[6:9], v[150:153], v[216:219], v[6:9]
	v_mfma_f32_16x16x32_bf16 v[2:5], v[158:161], v[216:219], v[2:5]
	s_barrier
	s_setprio 0
	s_add_i32 s4, 0, 0x18000
	s_add_i32 s5, 0, 0x1c000
	v_add_u32_e32 v142, s4, v171
	v_add_u32_e32 v158, s5, v171
	ds_read_b128 v[130:133], v142
	ds_read_b128 v[134:137], v142 offset:1024
	ds_read_b128 v[138:141], v142 offset:2048
	ds_read_b128 v[142:145], v142 offset:3072
	ds_read_b128 v[146:149], v158
	ds_read_b128 v[150:153], v158 offset:1024
	ds_read_b128 v[154:157], v158 offset:2048
	ds_read_b128 v[158:161], v158 offset:3072
	s_add_u32 s34, s34, 0xb0000
	s_addc_u32 s35, s35, 0
	s_mov_b32 m0, s74
	v_lshl_add_u64 v[240:241], s[34:35], 0, v[168:169]
	ds_read_b128 v[188:191], v233 offset:32768
	ds_read_b128 v[192:195], v233 offset:33792
	ds_read_b128 v[196:199], v233 offset:34816
	ds_read_b128 v[200:203], v233 offset:35840
	ds_read_b128 v[204:207], v233 offset:36864
	ds_read_b128 v[208:211], v233 offset:37888
	ds_read_b128 v[212:215], v233 offset:38912
	ds_read_b128 v[216:219], v233 offset:39936
	global_load_lds_dwordx4 v[240:241], off
	v_lshl_add_u64 v[240:241], s[34:35], 0, v[164:165]
	s_mov_b32 m0, s75
	s_nop 0
	global_load_lds_dwordx4 v[240:241], off
	s_waitcnt vmcnt(8)
	s_waitcnt lgkmcnt(0)
	s_setprio 1
	s_waitcnt lgkmcnt(0)
	s_barrier
	v_mfma_f32_16x16x32_bf16 v[126:129], v[130:133], v[188:191], v[126:129]
	v_mfma_f32_16x16x32_bf16 v[122:125], v[138:141], v[188:191], v[122:125]
	v_mfma_f32_16x16x32_bf16 v[110:113], v[130:133], v[196:199], v[110:113]
	v_mfma_f32_16x16x32_bf16 v[106:109], v[138:141], v[196:199], v[106:109]
	v_mfma_f32_16x16x32_bf16 v[94:97], v[130:133], v[204:207], v[94:97]
	v_mfma_f32_16x16x32_bf16 v[90:93], v[138:141], v[204:207], v[90:93]
	v_mfma_f32_16x16x32_bf16 v[78:81], v[130:133], v[212:215], v[78:81]
	v_mfma_f32_16x16x32_bf16 v[74:77], v[138:141], v[212:215], v[74:77]
	v_mfma_f32_16x16x32_bf16 v[126:129], v[134:137], v[192:195], v[126:129]
	v_mfma_f32_16x16x32_bf16 v[122:125], v[142:145], v[192:195], v[122:125]
	v_mfma_f32_16x16x32_bf16 v[110:113], v[134:137], v[200:203], v[110:113]
	v_mfma_f32_16x16x32_bf16 v[106:109], v[142:145], v[200:203], v[106:109]
	v_mfma_f32_16x16x32_bf16 v[94:97], v[134:137], v[208:211], v[94:97]
	v_mfma_f32_16x16x32_bf16 v[90:93], v[142:145], v[208:211], v[90:93]
	v_mfma_f32_16x16x32_bf16 v[78:81], v[134:137], v[216:219], v[78:81]
	v_mfma_f32_16x16x32_bf16 v[74:77], v[142:145], v[216:219], v[74:77]
	v_mfma_f32_16x16x32_bf16 v[118:121], v[146:149], v[188:191], v[118:121]
	v_mfma_f32_16x16x32_bf16 v[114:117], v[154:157], v[188:191], v[114:117]
	v_mfma_f32_16x16x32_bf16 v[102:105], v[146:149], v[196:199], v[102:105]
	v_mfma_f32_16x16x32_bf16 v[98:101], v[154:157], v[196:199], v[98:101]
	v_mfma_f32_16x16x32_bf16 v[86:89], v[146:149], v[204:207], v[86:89]
	v_mfma_f32_16x16x32_bf16 v[82:85], v[154:157], v[204:207], v[82:85]
	v_mfma_f32_16x16x32_bf16 v[70:73], v[146:149], v[212:215], v[70:73]
	v_mfma_f32_16x16x32_bf16 v[66:69], v[154:157], v[212:215], v[66:69]
	v_mfma_f32_16x16x32_bf16 v[118:121], v[150:153], v[192:195], v[118:121]
	v_mfma_f32_16x16x32_bf16 v[114:117], v[158:161], v[192:195], v[114:117]
	v_mfma_f32_16x16x32_bf16 v[102:105], v[150:153], v[200:203], v[102:105]
	v_mfma_f32_16x16x32_bf16 v[98:101], v[158:161], v[200:203], v[98:101]
	v_mfma_f32_16x16x32_bf16 v[86:89], v[150:153], v[208:211], v[86:89]
	v_mfma_f32_16x16x32_bf16 v[82:85], v[158:161], v[208:211], v[82:85]
	v_mfma_f32_16x16x32_bf16 v[70:73], v[150:153], v[216:219], v[70:73]
	v_mfma_f32_16x16x32_bf16 v[66:69], v[158:161], v[216:219], v[66:69]
	s_barrier
; #define PG8_STAGE(bufoff, gbase, voff) do { _Pragma("unroll") for (int _i = 0; _i < 2; ++_i) \
;         __builtin_amdgcn_global_load_lds((const unsigned*)((const char*)(gbase) + (voff)[_i]), (PG8_LAS unsigned*)(lds + (bufoff) + ldsw + _i * 8192), 16, 0, 0); } while (0)
; #define PG8_LDA(dst, b, h) do { _Pragma("unroll") for (int m = 0; m < 4; ++m) _Pragma("unroll") for (int k = 0; k < 2; ++k) dst[m][k] = *(const PG8_LAS bf16x8*)(lds + PG8_SA(b, h) + aoff + m * 2048 + k * 1024); } while (0)
; #define PG8_MMA(ai, bj, At, Bt) do { __builtin_amdgcn_s_setprio(1); _Pragma("unroll") for (int m = 0; m < 4; ++m) _Pragma("unroll") for (int n = 0; n < 2; ++n) _Pragma("unroll") for (int k = 0; k < 2; ++k) \
;         acc[ai][bj][m][n] = __builtin_amdgcn_mfma_f32_16x16x32_bf16(Bt[n][k], At[m][k], acc[ai][bj][m][n], 0, 0, 0); __builtin_amdgcn_s_setprio(0); } while (0)
; #define PG8_WAIT_V(n) asm volatile("s_waitcnt vmcnt(" #n ")" ::: "memory")
; #define PG8_WAIT_L(n) asm volatile("s_waitcnt lgkmcnt(" #n ")" ::: "memory")
; #define PG8_BAR __builtin_amdgcn_s_barrier()
; #define PG8_SCHED __builtin_amdgcn_sched_barrier(0)
; template <class Epi, class Sched, bool ALIGN_EPI = false, bool SP2 = false>
; __device__ __forceinline__ void gemm_phase(PG8_LAS unsigned char* lds, const Gemm g, const Sched& S, const Epi& E) {
;     ...
;             PG8_WAIT_V(8); PG8_WAIT_L(0); PG8_BAR; PG8_MMA(0, 0, At, B0); PG8_MMA(0, 1, At, B1); PG8_BAR; PG8_SCHED;
;             PG8_LDA(At, 1, 1); PG8_STAGE(PG8_SB(1, 0), b3, voffB); PG8_STAGE(PG8_SB(1, 1), b3 + hstepB, voffB); PG8_STAGE(PG8_SA(1, 0), a3, voffA);
;             PG8_WAIT_V(8); PG8_WAIT_L(0); PG8_BAR; PG8_MMA(1, 0, At, B0); PG8_MMA(1, 1, At, B1); PG8_BAR; PG8_SCHED;
;     ...
;         if constexpr (ALIGN_EPI) { if (wr == 0) PG8_BAR; }
	s_setprio 0
	s_add_i32 s4, s4, s61
	v_lshl_add_u64 v[220:221], v[220:221], 0, s[62:63]
	s_mov_b32 m0, s4
	ds_read_b128 v[188:191], v233 offset:49152
	ds_read_b128 v[192:195], v233 offset:50176
	ds_read_b128 v[196:199], v233 offset:51200
	ds_read_b128 v[200:203], v233 offset:52224
	ds_read_b128 v[204:207], v233 offset:53248
	ds_read_b128 v[208:211], v233 offset:54272
	ds_read_b128 v[212:215], v233 offset:55296
	ds_read_b128 v[216:219], v233 offset:56320
	global_load_lds_dwordx4 v[220:221], off
	s_add_i32 m0, s4, 0x2000
	s_add_u32 s24, s24, 0xb0080
	v_lshl_add_u64 v[220:221], v[234:235], 0, s[62:63]
	s_addc_u32 s25, s25, 0
	s_add_i32 s4, s5, s61
	global_load_lds_dwordx4 v[220:221], off
	v_lshl_add_u64 v[220:221], s[24:25], 0, v[166:167]
	s_mov_b32 m0, s4
	s_nop 0
	global_load_lds_dwordx4 v[220:221], off
	v_lshl_add_u64 v[220:221], s[24:25], 0, v[162:163]
	s_add_i32 m0, s4, 0x2000
	s_nop 0
	global_load_lds_dwordx4 v[220:221], off
	v_lshl_add_u64 v[220:221], v[236:237], 0, s[62:63]
	s_mov_b32 m0, s90
	s_nop 0
	global_load_lds_dwordx4 v[220:221], off
	v_lshl_add_u64 v[220:221], v[238:239], 0, s[62:63]
	s_mov_b32 m0, s91
	s_nop 0
	global_load_lds_dwordx4 v[220:221], off
	s_waitcnt vmcnt(8)
	s_waitcnt lgkmcnt(0)
	s_setprio 1
	s_waitcnt lgkmcnt(0)
	s_barrier
	v_mfma_f32_16x16x32_bf16 v[62:65], v[130:133], v[188:191], v[62:65]
	v_mfma_f32_16x16x32_bf16 v[58:61], v[138:141], v[188:191], v[58:61]
	v_mfma_f32_16x16x32_bf16 v[46:49], v[130:133], v[196:199], v[46:49]
	v_mfma_f32_16x16x32_bf16 v[42:45], v[138:141], v[196:199], v[42:45]
	v_mfma_f32_16x16x32_bf16 v[30:33], v[130:133], v[204:207], v[30:33]
	v_mfma_f32_16x16x32_bf16 v[26:29], v[138:141], v[204:207], v[26:29]
	v_mfma_f32_16x16x32_bf16 v[14:17], v[130:133], v[212:215], v[14:17]
	v_mfma_f32_16x16x32_bf16 v[10:13], v[138:141], v[212:215], v[10:13]
	v_mfma_f32_16x16x32_bf16 v[62:65], v[134:137], v[192:195], v[62:65]
	v_mfma_f32_16x16x32_bf16 v[58:61], v[142:145], v[192:195], v[58:61]
	v_mfma_f32_16x16x32_bf16 v[46:49], v[134:137], v[200:203], v[46:49]
	v_mfma_f32_16x16x32_bf16 v[42:45], v[142:145], v[200:203], v[42:45]
	v_mfma_f32_16x16x32_bf16 v[30:33], v[134:137], v[208:211], v[30:33]
	v_mfma_f32_16x16x32_bf16 v[26:29], v[142:145], v[208:211], v[26:29]
	v_mfma_f32_16x16x32_bf16 v[14:17], v[134:137], v[216:219], v[14:17]
	v_mfma_f32_16x16x32_bf16 v[10:13], v[142:145], v[216:219], v[10:13]
	v_mfma_f32_16x16x32_bf16 v[54:57], v[146:149], v[188:191], v[54:57]
	v_mfma_f32_16x16x32_bf16 v[50:53], v[154:157], v[188:191], v[50:53]
	v_mfma_f32_16x16x32_bf16 v[38:41], v[146:149], v[196:199], v[38:41]
	v_mfma_f32_16x16x32_bf16 v[34:37], v[154:157], v[196:199], v[34:37]
	v_mfma_f32_16x16x32_bf16 v[22:25], v[146:149], v[204:207], v[22:25]
	v_mfma_f32_16x16x32_bf16 v[18:21], v[154:157], v[204:207], v[18:21]
	v_mfma_f32_16x16x32_bf16 v[6:9], v[146:149], v[212:215], v[6:9]
	v_mfma_f32_16x16x32_bf16 v[2:5], v[154:157], v[212:215], v[2:5]
	v_mfma_f32_16x16x32_bf16 v[54:57], v[150:153], v[192:195], v[54:57]
	v_mfma_f32_16x16x32_bf16 v[50:53], v[158:161], v[192:195], v[50:53]
	v_mfma_f32_16x16x32_bf16 v[38:41], v[150:153], v[200:203], v[38:41]
	v_mfma_f32_16x16x32_bf16 v[34:37], v[158:161], v[200:203], v[34:37]
	v_mfma_f32_16x16x32_bf16 v[22:25], v[150:153], v[208:211], v[22:25]
	v_mfma_f32_16x16x32_bf16 v[18:21], v[158:161], v[208:211], v[18:21]
	v_mfma_f32_16x16x32_bf16 v[6:9], v[150:153], v[216:219], v[6:9]
	v_mfma_f32_16x16x32_bf16 v[2:5], v[158:161], v[216:219], v[2:5]
	s_barrier
	s_setprio 0
	s_add_i32 s76, s76, 2
	s_add_u32 s52, s52, 0x100
	s_addc_u32 s53, s53, 0
	s_cmp_gt_u32 s76, 41
	s_mov_b64 s[50:51], s[42:43]
	s_cbranch_scc0 .LBB0_971
	s_and_b64 vcc, exec, s[44:45]
	s_cbranch_vccz .LBB0_974
	s_barrier
